# G1/UP K-loops: 33 LDS-DMA tile loads use SGPR-base + 32-bit lane offset addressing instead of a v_lshl_add_u64 per load
# speedup vs baseline: 1.0165x; 1.0028x over previous
; #define PG8_STAGE(bufoff, gbase, voff) do { _Pragma("unroll") for (int _i = 0; _i < 2; ++_i) \
;         __builtin_amdgcn_global_load_lds((const unsigned*)((const char*)(gbase) + (voff)[_i]), (PG8_LAS unsigned*)(lds + (bufoff) + ldsw + _i * 8192), 16, 0, 0); } while (0)
; #define PG8_WAIT_V(n) asm volatile("s_waitcnt vmcnt(" #n ")" ::: "memory")
; #define PG8_BAR __builtin_amdgcn_s_barrier()
; template <class Epi, class Sched, bool ALIGN_EPI = false, bool SP2 = false>
; __device__ __forceinline__ void gemm_phase(PG8_LAS unsigned char* lds, const Gemm g, const Sched& S, const Epi& E) {
;     ...
;     for (int i = 0; i < 2; ++i) { int R, C; stage_rc(tid * 16 + i * 8192, R, C); const int Rb = Epi::PERM ? ((R & ~31) + perm32(R & 31)) : R;
;         voffA[i] = (unsigned)(R * LD + C) * 2u; voffB[i] = (unsigned)(Rb * LD + C) * 2u; }
;     const size_t kstep = (size_t)(BK * 2);
;     const size_t hstep = (size_t)HALF * LD * 2;
;     const size_t tstep = 2 * hstep;
;     const unsigned ldsw = (unsigned)wid * 1024u;
;     const int aoff = lds_byte(wr * 64 + fr, fq * 8), boff = lds_byte(wc * 32 + fr, fq * 8);
;     ...
;         PG8_STAGE(PG8_SB(1, 0), cB + kstep, voffB); PG8_STAGE(PG8_SA(1, 0), cA + kstep, voffA); PG8_STAGE(PG8_SB(1, 1), cB + hstep + kstep, voffB);
;         PG8_WAIT_V(6); PG8_BAR;
.LBB0_175:
	v_lshl_add_u64 v[10:11], s[18:19], 0, v[34:35]
	v_mov_b32_e32 v37, v35
	v_readlane_b32 s16, v254, 16
	s_lshl_b32 s4, s4, 5
	v_lshl_add_u64 v[12:13], s[18:19], 0, v[36:37]
	v_mov_b32_e32 v141, v35
	v_readlane_b32 s17, v254, 17
	s_and_b32 s7, s4, 0x60
	s_add_i32 m0, s25, 0x18000
	v_lshl_add_u64 v[10:11], v[10:11], 0, s[70:71]
	v_lshl_add_u64 v[14:15], s[16:17], 0, v[140:141]
	v_mov_b32_e32 v139, v35
	s_lshl_b32 s6, s1, 13
	s_lshl_b32 s8, s7, 7
	s_waitcnt vmcnt(2)
	s_barrier
	global_load_lds_dwordx4 v[10:11], off
	v_lshl_add_u64 v[10:11], v[12:13], 0, s[70:71]
	s_add_i32 m0, s25, 0x1a000
	s_add_i32 s29, s25, 0x8000
	s_add_i32 s30, s25, 0xa000
	v_lshl_add_u64 v[16:17], s[16:17], 0, v[138:139]
	global_load_lds_dwordx4 v[10:11], off
	v_lshl_add_u64 v[10:11], v[14:15], 0, s[70:71]
	s_mov_b32 m0, s29
	s_add_u32 s4, s18, 0x40080
	global_load_lds_dwordx4 v[10:11], off
	v_lshl_add_u64 v[10:11], v[16:17], 0, s[70:71]
	s_mov_b32 m0, s30
	s_addc_u32 s5, s19, 0
	global_load_lds_dwordx4 v[10:11], off
	s_add_i32 m0, s25, 0x1c000
	s_nop 0
	global_load_lds_dwordx4 v34, s[4:5]
	v_lshl_add_u64 v[10:11], s[4:5], 0, v[36:37]
	s_add_i32 m0, s25, 0x1e000
	v_and_b32_e32 v9, 15, v2
	global_load_lds_dwordx4 v[10:11], off
	v_lshrrev_b32_e32 v10, 1, v2
	v_and_b32_e32 v10, 24, v10
	v_lshlrev_b32_e32 v11, 1, v10
	v_lshlrev_b32_e32 v2, 2, v2
	v_lshl_or_b32 v150, s1, 6, v9
	v_lshl_or_b32 v9, v9, 6, v11
	v_and_b32_e32 v2, 32, v2
	v_bitop3_b32 v11, v9, s6, v2 bitop3:0xde
	v_bitop3_b32 v151, v9, s8, v2 bitop3:0xde
	v_lshlrev_b32_e32 v2, 14, v7
	v_and_b32_e32 v2, 0xffff8000, v2
	v_lshl_add_u32 v2, v6, 11, v2
	v_and_b32_e32 v6, 1, v7
	v_lshl_or_b32 v2, v6, 6, v2
	v_lshl_add_u32 v142, v8, 1, v2
	v_lshlrev_b32_e32 v2, 14, v3
	v_and_b32_e32 v2, 0xffff8000, v2
	s_waitcnt vmcnt(6)
	v_lshl_add_u32 v2, v4, 11, v2
	v_and_b32_e32 v3, 1, v3
	s_cmpk_lt_u32 s0, 0x100
	v_lshl_or_b32 v2, v3, 6, v2
	v_readlane_b32 s0, v254, 12
	s_cselect_b64 s[4:5], -1, 0
	v_or_b32_e32 v152, s7, v10
	v_mov_b32_e32 v143, v35
	v_lshl_add_u32 v144, v5, 1, v2
	v_mov_b32_e32 v145, v35
	s_mov_b32 s31, 0
	v_add_u32_e32 v153, 0, v11
	v_readlane_b32 s34, v254, 14
	s_mov_b32 s35, s0
	s_barrier
	v_readlane_b32 s1, v254, 13
	s_branch .LBB0_178

; #define PG8_STAGE(bufoff, gbase, voff) do { _Pragma("unroll") for (int _i = 0; _i < 2; ++_i) \
;         __builtin_amdgcn_global_load_lds((const unsigned*)((const char*)(gbase) + (voff)[_i]), (PG8_LAS unsigned*)(lds + (bufoff) + ldsw + _i * 8192), 16, 0, 0); } while (0)
; #define PG8_LDA(dst, b, h) do { _Pragma("unroll") for (int m = 0; m < 4; ++m) _Pragma("unroll") for (int k = 0; k < 2; ++k) dst[m][k] = *(const PG8_LAS bf16x8*)(lds + PG8_SA(b, h) + aoff + m * 2048 + k * 1024); } while (0)
; #define PG8_LDB(dst, b, h) do { _Pragma("unroll") for (int n = 0; n < 2; ++n) _Pragma("unroll") for (int k = 0; k < 2; ++k) dst[n][k] = *(const PG8_LAS bf16x8*)(lds + PG8_SB(b, h) + boff + n * 2048 + k * 1024); } while (0)
; #define PG8_MMA(ai, bj, At, Bt) do { __builtin_amdgcn_s_setprio(1); _Pragma("unroll") for (int m = 0; m < 4; ++m) _Pragma("unroll") for (int n = 0; n < 2; ++n) _Pragma("unroll") for (int k = 0; k < 2; ++k) \
;         acc[ai][bj][m][n] = __builtin_amdgcn_mfma_f32_16x16x32_bf16(Bt[n][k], At[m][k], acc[ai][bj][m][n], 0, 0, 0); __builtin_amdgcn_s_setprio(0); } while (0)
; #define PG8_WAIT_V(n) asm volatile("s_waitcnt vmcnt(" #n ")" ::: "memory")
; #define PG8_WAIT_L(n) asm volatile("s_waitcnt lgkmcnt(" #n ")" ::: "memory")
; #define PG8_BAR __builtin_amdgcn_s_barrier()
; #define PG8_SCHED __builtin_amdgcn_sched_barrier(0)
; template <class Epi, class Sched, bool ALIGN_EPI = false, bool SP2 = false>
; __device__ __forceinline__ void gemm_phase(PG8_LAS unsigned char* lds, const Gemm g, const Sched& S, const Epi& E) {
;     ...
;             PG8_LDB(B0, 0, 0); PG8_LDB(B1, 0, 1); PG8_SCHED; PG8_LDA(At, 0, 0); PG8_STAGE(PG8_SA(1, 1), a1 + hstep, voffA);
;             PG8_WAIT_V(8); PG8_WAIT_L(0); PG8_BAR; PG8_MMA(0, 0, At, B0); PG8_MMA(0, 1, At, B1); PG8_BAR; PG8_SCHED;
;             PG8_LDA(At, 0, 1); PG8_STAGE(PG8_SB(0, 0), b2, voffB); PG8_STAGE(PG8_SB(0, 1), b2 + hstep, voffB); PG8_STAGE(PG8_SA(0, 0), a2, voffA);
;             PG8_WAIT_V(8); PG8_WAIT_L(0); PG8_BAR; PG8_MMA(1, 0, At, B0); PG8_MMA(1, 1, At, B1); PG8_BAR; PG8_SCHED;
.LBB0_184:
	s_ashr_i32 s9, s8, 31
	s_lshl_b64 s[10:11], s[8:9], 19
	s_add_u32 s10, s90, s10
	s_addc_u32 s11, s91, s11
	s_and_b64 s[12:13], s[0:1], exec
	s_cselect_b32 s9, s11, s17
	s_cselect_b32 s36, s10, s16
	s_ashr_i32 s7, s6, 31
	s_lshl_b64 s[12:13], s[6:7], 19
	s_add_u32 s12, s22, s12
	s_addc_u32 s13, s23, s13
	s_and_b64 s[20:21], s[0:1], exec
	s_cselect_b32 s7, s13, s19
	s_cselect_b32 s37, s12, s18
	s_add_u32 s16, s16, 0x40080
	s_addc_u32 s17, s17, 0
	s_add_u32 s38, s18, 0x100
	s_addc_u32 s39, s19, 0
	s_mov_b32 s40, -2
	s_waitcnt vmcnt(0)
	s_add_u32 s18, s16, 0xfffc0080
	s_addc_u32 s19, s17, -1
	s_add_i32 s41, 0, 0x10000
	s_cmp_eq_u32 s40, 12
	s_cselect_b32 s21, s9, s19
	s_cselect_b32 s20, s36, s18
	v_add_u32_e32 v38, s41, v151
	s_cselect_b32 s19, s7, s39
	s_cselect_b32 s18, s37, s38
	s_add_i32 s44, 0, 0x14000
	ds_read_b128 v[146:149], v38
	ds_read_b128 v[154:157], v38 offset:1024
	ds_read_b128 v[158:161], v38 offset:2048
	ds_read_b128 v[162:165], v38 offset:3072
	v_add_u32_e32 v38, s44, v151
	ds_read_b128 v[166:169], v38
	ds_read_b128 v[170:173], v38 offset:1024
	ds_read_b128 v[174:177], v38 offset:2048
	ds_read_b128 v[178:181], v38 offset:3072
	s_add_i32 m0, s25, 0xc000
	ds_read_b128 v[186:189], v153
	ds_read_b128 v[190:193], v153 offset:1024
	ds_read_b128 v[194:197], v153 offset:2048
	ds_read_b128 v[198:201], v153 offset:3072
	ds_read_b128 v[226:229], v153 offset:4096
	ds_read_b128 v[230:233], v153 offset:5120
	ds_read_b128 v[234:237], v153 offset:6144
	ds_read_b128 v[238:241], v153 offset:7168
	global_load_lds_dwordx4 v142, s[16:17]
	s_add_i32 m0, s25, 0xe000
	s_nop 0
	global_load_lds_dwordx4 v144, s[16:17]
	s_waitcnt vmcnt(8)
	s_waitcnt lgkmcnt(0)
	s_barrier
	s_setprio 1
	s_waitcnt lgkmcnt(0)
	v_mfma_f32_16x16x32_bf16 v[134:137], v[146:149], v[186:189], 0
	v_mfma_f32_16x16x32_bf16 v[130:133], v[158:161], v[186:189], 0
	v_mfma_f32_16x16x32_bf16 v[126:129], v[146:149], v[194:197], 0
	v_mfma_f32_16x16x32_bf16 v[118:121], v[158:161], v[194:197], 0
	v_mfma_f32_16x16x32_bf16 v[110:113], v[146:149], v[226:229], 0
	v_mfma_f32_16x16x32_bf16 v[102:105], v[158:161], v[226:229], 0
	v_mfma_f32_16x16x32_bf16 v[94:97], v[146:149], v[234:237], 0
	v_mfma_f32_16x16x32_bf16 v[86:89], v[158:161], v[234:237], 0
	v_mfma_f32_16x16x32_bf16 v[134:137], v[154:157], v[190:193], v[134:137]
	v_mfma_f32_16x16x32_bf16 v[130:133], v[162:165], v[190:193], v[130:133]
	v_mfma_f32_16x16x32_bf16 v[126:129], v[154:157], v[198:201], v[126:129]
	v_mfma_f32_16x16x32_bf16 v[118:121], v[162:165], v[198:201], v[118:121]
	v_mfma_f32_16x16x32_bf16 v[110:113], v[154:157], v[230:233], v[110:113]
	v_mfma_f32_16x16x32_bf16 v[102:105], v[162:165], v[230:233], v[102:105]
	v_mfma_f32_16x16x32_bf16 v[94:97], v[154:157], v[238:241], v[94:97]
	v_mfma_f32_16x16x32_bf16 v[86:89], v[162:165], v[238:241], v[86:89]
	s_setprio 0
	s_setprio 1
	v_mfma_f32_16x16x32_bf16 v[122:125], v[166:169], v[186:189], 0
	v_mfma_f32_16x16x32_bf16 v[114:117], v[174:177], v[186:189], 0
	v_mfma_f32_16x16x32_bf16 v[106:109], v[166:169], v[194:197], 0
	v_mfma_f32_16x16x32_bf16 v[98:101], v[174:177], v[194:197], 0
	v_mfma_f32_16x16x32_bf16 v[90:93], v[166:169], v[226:229], 0
	v_mfma_f32_16x16x32_bf16 v[82:85], v[174:177], v[226:229], 0
	v_mfma_f32_16x16x32_bf16 v[78:81], v[166:169], v[234:237], 0
	v_mfma_f32_16x16x32_bf16 v[74:77], v[174:177], v[234:237], 0
	v_mfma_f32_16x16x32_bf16 v[122:125], v[170:173], v[190:193], v[122:125]
	v_mfma_f32_16x16x32_bf16 v[114:117], v[178:181], v[190:193], v[114:117]
	v_mfma_f32_16x16x32_bf16 v[106:109], v[170:173], v[198:201], v[106:109]
	v_mfma_f32_16x16x32_bf16 v[98:101], v[178:181], v[198:201], v[98:101]
	v_mfma_f32_16x16x32_bf16 v[90:93], v[170:173], v[230:233], v[90:93]
	v_mfma_f32_16x16x32_bf16 v[82:85], v[178:181], v[230:233], v[82:85]
	v_mfma_f32_16x16x32_bf16 v[78:81], v[170:173], v[238:241], v[78:81]
	v_mfma_f32_16x16x32_bf16 v[74:77], v[178:181], v[238:241], v[74:77]
	s_setprio 0
	s_barrier
	s_add_i32 s41, s41, s24
	v_lshl_add_u64 v[202:203], s[18:19], 0, v[34:35]
	s_mov_b32 m0, s41
	ds_read_b128 v[186:189], v153 offset:16384
	ds_read_b128 v[190:193], v153 offset:17408
	ds_read_b128 v[194:197], v153 offset:18432
	ds_read_b128 v[198:201], v153 offset:19456
	ds_read_b128 v[226:229], v153 offset:20480
	ds_read_b128 v[230:233], v153 offset:21504
	ds_read_b128 v[234:237], v153 offset:22528
	ds_read_b128 v[238:241], v153 offset:23552
	global_load_lds_dwordx4 v[202:203], off
	s_add_i32 m0, s41, 0x2000
	s_add_u32 s42, s18, 0x40000
	v_lshl_add_u64 v[208:209], s[18:19], 0, v[36:37]
	s_addc_u32 s43, s19, 0
	s_add_i32 s41, s44, s24
	global_load_lds_dwordx4 v[208:209], off
	s_mov_b32 m0, s41
	v_lshl_add_u64 v[218:219], s[20:21], 0, v[138:139]
	global_load_lds_dwordx4 v34, s[42:43]
	s_add_i32 m0, s41, 0x2000
	s_nop 0
	global_load_lds_dwordx4 v36, s[42:43]
	v_lshl_add_u64 v[210:211], s[20:21], 0, v[140:141]
	s_mov_b32 m0, s25
	s_nop 0
	global_load_lds_dwordx4 v[210:211], off
	s_mov_b32 m0, s26
	s_nop 0
	global_load_lds_dwordx4 v[218:219], off
	s_waitcnt vmcnt(8)
	s_waitcnt lgkmcnt(0)
	s_barrier
; #define PG8_STAGE(bufoff, gbase, voff) do { _Pragma("unroll") for (int _i = 0; _i < 2; ++_i) \
;         __builtin_amdgcn_global_load_lds((const unsigned*)((const char*)(gbase) + (voff)[_i]), (PG8_LAS unsigned*)(lds + (bufoff) + ldsw + _i * 8192), 16, 0, 0); } while (0)
; #define PG8_LDA(dst, b, h) do { _Pragma("unroll") for (int m = 0; m < 4; ++m) _Pragma("unroll") for (int k = 0; k < 2; ++k) dst[m][k] = *(const PG8_LAS bf16x8*)(lds + PG8_SA(b, h) + aoff + m * 2048 + k * 1024); } while (0)
; #define PG8_LDB(dst, b, h) do { _Pragma("unroll") for (int n = 0; n < 2; ++n) _Pragma("unroll") for (int k = 0; k < 2; ++k) dst[n][k] = *(const PG8_LAS bf16x8*)(lds + PG8_SB(b, h) + boff + n * 2048 + k * 1024); } while (0)
; #define PG8_MMA(ai, bj, At, Bt) do { __builtin_amdgcn_s_setprio(1); _Pragma("unroll") for (int m = 0; m < 4; ++m) _Pragma("unroll") for (int n = 0; n < 2; ++n) _Pragma("unroll") for (int k = 0; k < 2; ++k) \
;         acc[ai][bj][m][n] = __builtin_amdgcn_mfma_f32_16x16x32_bf16(Bt[n][k], At[m][k], acc[ai][bj][m][n], 0, 0, 0); __builtin_amdgcn_s_setprio(0); } while (0)
; #define PG8_WAIT_V(n) asm volatile("s_waitcnt vmcnt(" #n ")" ::: "memory")
; #define PG8_WAIT_L(n) asm volatile("s_waitcnt lgkmcnt(" #n ")" ::: "memory")
; #define PG8_BAR __builtin_amdgcn_s_barrier()
; #define PG8_SCHED __builtin_amdgcn_sched_barrier(0)
; template <class Epi, class Sched, bool ALIGN_EPI = false, bool SP2 = false>
; __device__ __forceinline__ void gemm_phase(PG8_LAS unsigned char* lds, const Gemm g, const Sched& S, const Epi& E) {
;     ...
;             PG8_WAIT_V(8); PG8_WAIT_L(0); PG8_BAR; PG8_MMA(1, 0, At, B0); PG8_MMA(1, 1, At, B1); PG8_BAR; PG8_SCHED;
;             PG8_LDB(B0, 1, 0); PG8_LDB(B1, 1, 1); PG8_SCHED; PG8_LDA(At, 1, 0); PG8_STAGE(PG8_SA(0, 1), a2 + hstep, voffA);
;             PG8_WAIT_V(8); PG8_WAIT_L(0); PG8_BAR; PG8_MMA(0, 0, At, B0); PG8_MMA(0, 1, At, B1); PG8_BAR; PG8_SCHED;
	s_setprio 1
	s_waitcnt lgkmcnt(0)
	v_mfma_f32_16x16x32_bf16 v[70:73], v[146:149], v[186:189], 0
	v_mfma_f32_16x16x32_bf16 v[66:69], v[158:161], v[186:189], 0
	v_mfma_f32_16x16x32_bf16 v[62:65], v[146:149], v[194:197], 0
	v_mfma_f32_16x16x32_bf16 v[54:57], v[158:161], v[194:197], 0
	v_mfma_f32_16x16x32_bf16 v[46:49], v[146:149], v[226:229], 0
	v_mfma_f32_16x16x32_bf16 v[30:33], v[158:161], v[226:229], 0
	v_mfma_f32_16x16x32_bf16 v[22:25], v[146:149], v[234:237], 0
	v_mfma_f32_16x16x32_bf16 v[14:17], v[158:161], v[234:237], 0
	v_mfma_f32_16x16x32_bf16 v[70:73], v[154:157], v[190:193], v[70:73]
	v_mfma_f32_16x16x32_bf16 v[66:69], v[162:165], v[190:193], v[66:69]
	v_mfma_f32_16x16x32_bf16 v[62:65], v[154:157], v[198:201], v[62:65]
	v_mfma_f32_16x16x32_bf16 v[54:57], v[162:165], v[198:201], v[54:57]
	v_mfma_f32_16x16x32_bf16 v[46:49], v[154:157], v[230:233], v[46:49]
	v_mfma_f32_16x16x32_bf16 v[30:33], v[162:165], v[230:233], v[30:33]
	v_mfma_f32_16x16x32_bf16 v[22:25], v[154:157], v[238:241], v[22:25]
	v_mfma_f32_16x16x32_bf16 v[14:17], v[162:165], v[238:241], v[14:17]
	s_setprio 0
	s_setprio 1
	v_mfma_f32_16x16x32_bf16 v[58:61], v[166:169], v[186:189], 0
	v_mfma_f32_16x16x32_bf16 v[50:53], v[174:177], v[186:189], 0
	v_mfma_f32_16x16x32_bf16 v[42:45], v[166:169], v[194:197], 0
	v_mfma_f32_16x16x32_bf16 v[26:29], v[174:177], v[194:197], 0
	v_mfma_f32_16x16x32_bf16 v[18:21], v[166:169], v[226:229], 0
	v_mfma_f32_16x16x32_bf16 v[10:13], v[174:177], v[226:229], 0
	v_mfma_f32_16x16x32_bf16 v[6:9], v[166:169], v[234:237], 0
	v_mfma_f32_16x16x32_bf16 v[2:5], v[174:177], v[234:237], 0
	v_mfma_f32_16x16x32_bf16 v[58:61], v[170:173], v[190:193], v[58:61]
	v_mfma_f32_16x16x32_bf16 v[50:53], v[178:181], v[190:193], v[50:53]
	v_mfma_f32_16x16x32_bf16 v[42:45], v[170:173], v[198:201], v[42:45]
	v_mfma_f32_16x16x32_bf16 v[26:29], v[178:181], v[198:201], v[26:29]
	v_mfma_f32_16x16x32_bf16 v[18:21], v[170:173], v[230:233], v[18:21]
	v_mfma_f32_16x16x32_bf16 v[10:13], v[178:181], v[230:233], v[10:13]
	v_mfma_f32_16x16x32_bf16 v[6:9], v[170:173], v[238:241], v[6:9]
	v_mfma_f32_16x16x32_bf16 v[2:5], v[178:181], v[238:241], v[2:5]
	s_setprio 0
	s_barrier
	s_add_i32 s41, 0, 0x18000
	v_add_u32_e32 v38, s41, v151
	s_add_i32 s42, 0, 0x1c000
	ds_read_b128 v[146:149], v38
	ds_read_b128 v[154:157], v38 offset:1024
	ds_read_b128 v[158:161], v38 offset:2048
	ds_read_b128 v[162:165], v38 offset:3072
	v_add_u32_e32 v38, s42, v151
	ds_read_b128 v[166:169], v38
	ds_read_b128 v[170:173], v38 offset:1024
	ds_read_b128 v[174:177], v38 offset:2048
	ds_read_b128 v[178:181], v38 offset:3072
	s_add_u32 s20, s20, 0x40000
	s_addc_u32 s21, s21, 0
	s_mov_b32 m0, s27
	ds_read_b128 v[186:189], v153 offset:32768
	ds_read_b128 v[190:193], v153 offset:33792
	ds_read_b128 v[194:197], v153 offset:34816
	ds_read_b128 v[198:201], v153 offset:35840
	ds_read_b128 v[226:229], v153 offset:36864
	ds_read_b128 v[230:233], v153 offset:37888
	ds_read_b128 v[234:237], v153 offset:38912
	ds_read_b128 v[238:241], v153 offset:39936
	global_load_lds_dwordx4 v140, s[20:21]
	s_mov_b32 m0, s28
	s_nop 0
	global_load_lds_dwordx4 v138, s[20:21]
	s_waitcnt vmcnt(8)
	s_waitcnt lgkmcnt(0)
	s_barrier
	s_setprio 1
	s_waitcnt lgkmcnt(0)
	v_mfma_f32_16x16x32_bf16 v[134:137], v[146:149], v[186:189], v[134:137]
	v_mfma_f32_16x16x32_bf16 v[130:133], v[158:161], v[186:189], v[130:133]
	v_mfma_f32_16x16x32_bf16 v[126:129], v[146:149], v[194:197], v[126:129]
	v_mfma_f32_16x16x32_bf16 v[118:121], v[158:161], v[194:197], v[118:121]
	v_mfma_f32_16x16x32_bf16 v[110:113], v[146:149], v[226:229], v[110:113]
	v_mfma_f32_16x16x32_bf16 v[102:105], v[158:161], v[226:229], v[102:105]
	v_mfma_f32_16x16x32_bf16 v[94:97], v[146:149], v[234:237], v[94:97]
	v_mfma_f32_16x16x32_bf16 v[86:89], v[158:161], v[234:237], v[86:89]
	v_mfma_f32_16x16x32_bf16 v[134:137], v[154:157], v[190:193], v[134:137]
	v_mfma_f32_16x16x32_bf16 v[130:133], v[162:165], v[190:193], v[130:133]
	v_mfma_f32_16x16x32_bf16 v[126:129], v[154:157], v[198:201], v[126:129]
	v_mfma_f32_16x16x32_bf16 v[118:121], v[162:165], v[198:201], v[118:121]
	v_mfma_f32_16x16x32_bf16 v[110:113], v[154:157], v[230:233], v[110:113]
	v_mfma_f32_16x16x32_bf16 v[102:105], v[162:165], v[230:233], v[102:105]
	v_mfma_f32_16x16x32_bf16 v[94:97], v[154:157], v[238:241], v[94:97]
	v_mfma_f32_16x16x32_bf16 v[86:89], v[162:165], v[238:241], v[86:89]
	s_setprio 0
	s_setprio 1
	v_mfma_f32_16x16x32_bf16 v[122:125], v[166:169], v[186:189], v[122:125]
	v_mfma_f32_16x16x32_bf16 v[114:117], v[174:177], v[186:189], v[114:117]
	v_mfma_f32_16x16x32_bf16 v[106:109], v[166:169], v[194:197], v[106:109]
	v_mfma_f32_16x16x32_bf16 v[98:101], v[174:177], v[194:197], v[98:101]
	v_mfma_f32_16x16x32_bf16 v[90:93], v[166:169], v[226:229], v[90:93]
	v_mfma_f32_16x16x32_bf16 v[82:85], v[174:177], v[226:229], v[82:85]
	v_mfma_f32_16x16x32_bf16 v[78:81], v[166:169], v[234:237], v[78:81]
	v_mfma_f32_16x16x32_bf16 v[74:77], v[174:177], v[234:237], v[74:77]
	v_mfma_f32_16x16x32_bf16 v[122:125], v[170:173], v[190:193], v[122:125]
	v_mfma_f32_16x16x32_bf16 v[114:117], v[178:181], v[190:193], v[114:117]
	v_mfma_f32_16x16x32_bf16 v[106:109], v[170:173], v[198:201], v[106:109]
	v_mfma_f32_16x16x32_bf16 v[98:101], v[178:181], v[198:201], v[98:101]
	v_mfma_f32_16x16x32_bf16 v[90:93], v[170:173], v[230:233], v[90:93]
	v_mfma_f32_16x16x32_bf16 v[82:85], v[178:181], v[230:233], v[82:85]
	v_mfma_f32_16x16x32_bf16 v[78:81], v[170:173], v[238:241], v[78:81]
	v_mfma_f32_16x16x32_bf16 v[74:77], v[178:181], v[238:241], v[74:77]
	s_setprio 0
	s_barrier
; #define PG8_STAGE(bufoff, gbase, voff) do { _Pragma("unroll") for (int _i = 0; _i < 2; ++_i) \
;         __builtin_amdgcn_global_load_lds((const unsigned*)((const char*)(gbase) + (voff)[_i]), (PG8_LAS unsigned*)(lds + (bufoff) + ldsw + _i * 8192), 16, 0, 0); } while (0)
; #define PG8_LDA(dst, b, h) do { _Pragma("unroll") for (int m = 0; m < 4; ++m) _Pragma("unroll") for (int k = 0; k < 2; ++k) dst[m][k] = *(const PG8_LAS bf16x8*)(lds + PG8_SA(b, h) + aoff + m * 2048 + k * 1024); } while (0)
; #define PG8_LDB(dst, b, h) do { _Pragma("unroll") for (int n = 0; n < 2; ++n) _Pragma("unroll") for (int k = 0; k < 2; ++k) dst[n][k] = *(const PG8_LAS bf16x8*)(lds + PG8_SB(b, h) + boff + n * 2048 + k * 1024); } while (0)
; #define PG8_MMA(ai, bj, At, Bt) do { __builtin_amdgcn_s_setprio(1); _Pragma("unroll") for (int m = 0; m < 4; ++m) _Pragma("unroll") for (int n = 0; n < 2; ++n) _Pragma("unroll") for (int k = 0; k < 2; ++k) \
;         acc[ai][bj][m][n] = __builtin_amdgcn_mfma_f32_16x16x32_bf16(Bt[n][k], At[m][k], acc[ai][bj][m][n], 0, 0, 0); __builtin_amdgcn_s_setprio(0); } while (0)
; #define PG8_WAIT_V(n) asm volatile("s_waitcnt vmcnt(" #n ")" ::: "memory")
; #define PG8_WAIT_L(n) asm volatile("s_waitcnt lgkmcnt(" #n ")" ::: "memory")
; #define PG8_BAR __builtin_amdgcn_s_barrier()
; #define PG8_SCHED __builtin_amdgcn_sched_barrier(0)
; template <class Epi, class Sched, bool ALIGN_EPI = false, bool SP2 = false>
; __device__ __forceinline__ void gemm_phase(PG8_LAS unsigned char* lds, const Gemm g, const Sched& S, const Epi& E) {
;     ...
;             PG8_LDB(B0, 0, 0); PG8_LDB(B1, 0, 1); PG8_SCHED; PG8_LDA(At, 0, 0); PG8_STAGE(PG8_SA(1, 1), a1 + hstep, voffA);
;             PG8_WAIT_V(8); PG8_WAIT_L(0); PG8_BAR; PG8_MMA(0, 0, At, B0); PG8_MMA(0, 1, At, B1); PG8_BAR; PG8_SCHED;
;             PG8_LDA(At, 0, 1); PG8_STAGE(PG8_SB(0, 0), b2, voffB); PG8_STAGE(PG8_SB(0, 1), b2 + hstep, voffB); PG8_STAGE(PG8_SA(0, 0), a2, voffA);
;             PG8_WAIT_V(8); PG8_WAIT_L(0); PG8_BAR; PG8_MMA(1, 0, At, B0); PG8_MMA(1, 1, At, B1); PG8_BAR; PG8_SCHED;
;     ...
;             PG8_LDA(At, 1, 1); PG8_STAGE(PG8_SB(1, 0), b3, voffB); PG8_STAGE(PG8_SB(1, 1), b3 + hstep, voffB); PG8_STAGE(PG8_SA(1, 0), a3, voffA);
;             PG8_WAIT_V(8); PG8_WAIT_L(0); PG8_BAR; PG8_MMA(1, 0, At, B0); PG8_MMA(1, 1, At, B1); PG8_BAR; PG8_SCHED;
	s_add_i32 s20, s41, s24
	v_lshl_add_u64 v[202:203], v[202:203], 0, s[70:71]
	s_mov_b32 m0, s20
	ds_read_b128 v[186:189], v153 offset:49152
	ds_read_b128 v[190:193], v153 offset:50176
	ds_read_b128 v[194:197], v153 offset:51200
	ds_read_b128 v[198:201], v153 offset:52224
	ds_read_b128 v[226:229], v153 offset:53248
	ds_read_b128 v[230:233], v153 offset:54272
	ds_read_b128 v[234:237], v153 offset:55296
	ds_read_b128 v[238:241], v153 offset:56320
	global_load_lds_dwordx4 v[202:203], off
	s_add_i32 m0, s20, 0x2000
	s_add_u32 s18, s18, 0x40080
	v_lshl_add_u64 v[202:203], v[208:209], 0, s[70:71]
	s_addc_u32 s19, s19, 0
	s_add_i32 s20, s42, s24
	global_load_lds_dwordx4 v[202:203], off
	s_mov_b32 m0, s20
	s_nop 0
	global_load_lds_dwordx4 v34, s[18:19]
	s_add_i32 m0, s20, 0x2000
	s_nop 0
	global_load_lds_dwordx4 v36, s[18:19]
	v_lshl_add_u64 v[202:203], v[210:211], 0, s[70:71]
	s_mov_b32 m0, s29
	s_nop 0
	global_load_lds_dwordx4 v[202:203], off
	v_lshl_add_u64 v[202:203], v[218:219], 0, s[70:71]
	s_mov_b32 m0, s30
	s_nop 0
	global_load_lds_dwordx4 v[202:203], off
	s_waitcnt vmcnt(8)
	s_waitcnt lgkmcnt(0)
	s_barrier
	s_setprio 1
	s_waitcnt lgkmcnt(0)
	v_mfma_f32_16x16x32_bf16 v[70:73], v[146:149], v[186:189], v[70:73]
	v_mfma_f32_16x16x32_bf16 v[66:69], v[158:161], v[186:189], v[66:69]
	v_mfma_f32_16x16x32_bf16 v[62:65], v[146:149], v[194:197], v[62:65]
	v_mfma_f32_16x16x32_bf16 v[54:57], v[158:161], v[194:197], v[54:57]
	v_mfma_f32_16x16x32_bf16 v[46:49], v[146:149], v[226:229], v[46:49]
	v_mfma_f32_16x16x32_bf16 v[30:33], v[158:161], v[226:229], v[30:33]
	v_mfma_f32_16x16x32_bf16 v[22:25], v[146:149], v[234:237], v[22:25]
	v_mfma_f32_16x16x32_bf16 v[14:17], v[158:161], v[234:237], v[14:17]
	v_mfma_f32_16x16x32_bf16 v[70:73], v[154:157], v[190:193], v[70:73]
	v_mfma_f32_16x16x32_bf16 v[66:69], v[162:165], v[190:193], v[66:69]
	v_mfma_f32_16x16x32_bf16 v[62:65], v[154:157], v[198:201], v[62:65]
	v_mfma_f32_16x16x32_bf16 v[54:57], v[162:165], v[198:201], v[54:57]
	v_mfma_f32_16x16x32_bf16 v[46:49], v[154:157], v[230:233], v[46:49]
	v_mfma_f32_16x16x32_bf16 v[30:33], v[162:165], v[230:233], v[30:33]
	v_mfma_f32_16x16x32_bf16 v[22:25], v[154:157], v[238:241], v[22:25]
	v_mfma_f32_16x16x32_bf16 v[14:17], v[162:165], v[238:241], v[14:17]
	s_setprio 0
	s_setprio 1
	v_mfma_f32_16x16x32_bf16 v[58:61], v[166:169], v[186:189], v[58:61]
	v_mfma_f32_16x16x32_bf16 v[50:53], v[174:177], v[186:189], v[50:53]
	v_mfma_f32_16x16x32_bf16 v[42:45], v[166:169], v[194:197], v[42:45]
	v_mfma_f32_16x16x32_bf16 v[26:29], v[174:177], v[194:197], v[26:29]
	v_mfma_f32_16x16x32_bf16 v[18:21], v[166:169], v[226:229], v[18:21]
	v_mfma_f32_16x16x32_bf16 v[10:13], v[174:177], v[226:229], v[10:13]
	v_mfma_f32_16x16x32_bf16 v[6:9], v[166:169], v[234:237], v[6:9]
	v_mfma_f32_16x16x32_bf16 v[2:5], v[174:177], v[234:237], v[2:5]
	v_mfma_f32_16x16x32_bf16 v[58:61], v[170:173], v[190:193], v[58:61]
	v_mfma_f32_16x16x32_bf16 v[50:53], v[178:181], v[190:193], v[50:53]
	v_mfma_f32_16x16x32_bf16 v[42:45], v[170:173], v[198:201], v[42:45]
	v_mfma_f32_16x16x32_bf16 v[26:29], v[178:181], v[198:201], v[26:29]
	v_mfma_f32_16x16x32_bf16 v[18:21], v[170:173], v[230:233], v[18:21]
	v_mfma_f32_16x16x32_bf16 v[10:13], v[178:181], v[230:233], v[10:13]
	v_mfma_f32_16x16x32_bf16 v[6:9], v[170:173], v[238:241], v[6:9]
	v_mfma_f32_16x16x32_bf16 v[2:5], v[178:181], v[238:241], v[2:5]
	s_setprio 0
	s_barrier
	s_add_i32 s40, s40, 2
	s_add_u32 s16, s16, 0x100
	s_addc_u32 s17, s17, 0
	s_add_u32 s38, s38, 0x100
	s_addc_u32 s39, s39, 0
	s_cmp_gt_u32 s40, 13
.LBB0_185:
	s_add_u32 s18, s16, 0xfffc0080
	s_addc_u32 s19, s17, -1
	s_add_i32 s41, 0, 0x10000
	s_cmp_eq_u32 s40, 12
	s_cselect_b32 s21, s9, s19
	s_cselect_b32 s20, s36, s18
	v_add_u32_e32 v38, s41, v151
	s_cselect_b32 s19, s7, s39
	s_cselect_b32 s18, s37, s38
	s_add_i32 s44, 0, 0x14000
	ds_read_b128 v[146:149], v38
	ds_read_b128 v[154:157], v38 offset:1024
	ds_read_b128 v[158:161], v38 offset:2048
	ds_read_b128 v[162:165], v38 offset:3072
	v_add_u32_e32 v38, s44, v151
	ds_read_b128 v[166:169], v38
	ds_read_b128 v[170:173], v38 offset:1024
	ds_read_b128 v[174:177], v38 offset:2048
	ds_read_b128 v[178:181], v38 offset:3072
	s_add_i32 m0, s25, 0xc000
	ds_read_b128 v[186:189], v153
	ds_read_b128 v[190:193], v153 offset:1024
	ds_read_b128 v[194:197], v153 offset:2048
	ds_read_b128 v[198:201], v153 offset:3072
	ds_read_b128 v[226:229], v153 offset:4096
	ds_read_b128 v[230:233], v153 offset:5120
	ds_read_b128 v[234:237], v153 offset:6144
	ds_read_b128 v[238:241], v153 offset:7168
	global_load_lds_dwordx4 v142, s[16:17]
	s_add_i32 m0, s25, 0xe000
	s_nop 0
	global_load_lds_dwordx4 v144, s[16:17]
	s_waitcnt vmcnt(8)
	s_waitcnt lgkmcnt(0)
	s_barrier
; #define PG8_STAGE(bufoff, gbase, voff) do { _Pragma("unroll") for (int _i = 0; _i < 2; ++_i) \
;         __builtin_amdgcn_global_load_lds((const unsigned*)((const char*)(gbase) + (voff)[_i]), (PG8_LAS unsigned*)(lds + (bufoff) + ldsw + _i * 8192), 16, 0, 0); } while (0)
; #define PG8_LDA(dst, b, h) do { _Pragma("unroll") for (int m = 0; m < 4; ++m) _Pragma("unroll") for (int k = 0; k < 2; ++k) dst[m][k] = *(const PG8_LAS bf16x8*)(lds + PG8_SA(b, h) + aoff + m * 2048 + k * 1024); } while (0)
; #define PG8_MMA(ai, bj, At, Bt) do { __builtin_amdgcn_s_setprio(1); _Pragma("unroll") for (int m = 0; m < 4; ++m) _Pragma("unroll") for (int n = 0; n < 2; ++n) _Pragma("unroll") for (int k = 0; k < 2; ++k) \
;         acc[ai][bj][m][n] = __builtin_amdgcn_mfma_f32_16x16x32_bf16(Bt[n][k], At[m][k], acc[ai][bj][m][n], 0, 0, 0); __builtin_amdgcn_s_setprio(0); } while (0)
; #define PG8_WAIT_V(n) asm volatile("s_waitcnt vmcnt(" #n ")" ::: "memory")
; #define PG8_WAIT_L(n) asm volatile("s_waitcnt lgkmcnt(" #n ")" ::: "memory")
; #define PG8_BAR __builtin_amdgcn_s_barrier()
; #define PG8_SCHED __builtin_amdgcn_sched_barrier(0)
; template <class Epi, class Sched, bool ALIGN_EPI = false, bool SP2 = false>
; __device__ __forceinline__ void gemm_phase(PG8_LAS unsigned char* lds, const Gemm g, const Sched& S, const Epi& E) {
;     ...
;             PG8_WAIT_V(8); PG8_WAIT_L(0); PG8_BAR; PG8_MMA(0, 0, At, B0); PG8_MMA(0, 1, At, B1); PG8_BAR; PG8_SCHED;
;             PG8_LDA(At, 0, 1); PG8_STAGE(PG8_SB(0, 0), b2, voffB); PG8_STAGE(PG8_SB(0, 1), b2 + hstep, voffB); PG8_STAGE(PG8_SA(0, 0), a2, voffA);
;             PG8_WAIT_V(8); PG8_WAIT_L(0); PG8_BAR; PG8_MMA(1, 0, At, B0); PG8_MMA(1, 1, At, B1); PG8_BAR; PG8_SCHED;
	s_setprio 1
	s_waitcnt lgkmcnt(0)
	v_mfma_f32_16x16x32_bf16 v[134:137], v[146:149], v[186:189], v[134:137]
	v_mfma_f32_16x16x32_bf16 v[130:133], v[158:161], v[186:189], v[130:133]
	v_mfma_f32_16x16x32_bf16 v[126:129], v[146:149], v[194:197], v[126:129]
	v_mfma_f32_16x16x32_bf16 v[118:121], v[158:161], v[194:197], v[118:121]
	v_mfma_f32_16x16x32_bf16 v[110:113], v[146:149], v[226:229], v[110:113]
	v_mfma_f32_16x16x32_bf16 v[102:105], v[158:161], v[226:229], v[102:105]
	v_mfma_f32_16x16x32_bf16 v[94:97], v[146:149], v[234:237], v[94:97]
	v_mfma_f32_16x16x32_bf16 v[86:89], v[158:161], v[234:237], v[86:89]
	v_mfma_f32_16x16x32_bf16 v[134:137], v[154:157], v[190:193], v[134:137]
	v_mfma_f32_16x16x32_bf16 v[130:133], v[162:165], v[190:193], v[130:133]
	v_mfma_f32_16x16x32_bf16 v[126:129], v[154:157], v[198:201], v[126:129]
	v_mfma_f32_16x16x32_bf16 v[118:121], v[162:165], v[198:201], v[118:121]
	v_mfma_f32_16x16x32_bf16 v[110:113], v[154:157], v[230:233], v[110:113]
	v_mfma_f32_16x16x32_bf16 v[102:105], v[162:165], v[230:233], v[102:105]
	v_mfma_f32_16x16x32_bf16 v[94:97], v[154:157], v[238:241], v[94:97]
	v_mfma_f32_16x16x32_bf16 v[86:89], v[162:165], v[238:241], v[86:89]
	s_setprio 0
	s_setprio 1
	v_mfma_f32_16x16x32_bf16 v[122:125], v[166:169], v[186:189], v[122:125]
	v_mfma_f32_16x16x32_bf16 v[114:117], v[174:177], v[186:189], v[114:117]
	v_mfma_f32_16x16x32_bf16 v[106:109], v[166:169], v[194:197], v[106:109]
	v_mfma_f32_16x16x32_bf16 v[98:101], v[174:177], v[194:197], v[98:101]
	v_mfma_f32_16x16x32_bf16 v[90:93], v[166:169], v[226:229], v[90:93]
	v_mfma_f32_16x16x32_bf16 v[82:85], v[174:177], v[226:229], v[82:85]
	v_mfma_f32_16x16x32_bf16 v[78:81], v[166:169], v[234:237], v[78:81]
	v_mfma_f32_16x16x32_bf16 v[74:77], v[174:177], v[234:237], v[74:77]
	v_mfma_f32_16x16x32_bf16 v[122:125], v[170:173], v[190:193], v[122:125]
	v_mfma_f32_16x16x32_bf16 v[114:117], v[178:181], v[190:193], v[114:117]
	v_mfma_f32_16x16x32_bf16 v[106:109], v[170:173], v[198:201], v[106:109]
	v_mfma_f32_16x16x32_bf16 v[98:101], v[178:181], v[198:201], v[98:101]
	v_mfma_f32_16x16x32_bf16 v[90:93], v[170:173], v[230:233], v[90:93]
	v_mfma_f32_16x16x32_bf16 v[82:85], v[178:181], v[230:233], v[82:85]
	v_mfma_f32_16x16x32_bf16 v[78:81], v[170:173], v[238:241], v[78:81]
	v_mfma_f32_16x16x32_bf16 v[74:77], v[178:181], v[238:241], v[74:77]
	s_setprio 0
	s_barrier
	s_add_i32 s41, s41, s24
	v_lshl_add_u64 v[202:203], s[18:19], 0, v[34:35]
	s_mov_b32 m0, s41
	ds_read_b128 v[186:189], v153 offset:16384
	ds_read_b128 v[190:193], v153 offset:17408
	ds_read_b128 v[194:197], v153 offset:18432
	ds_read_b128 v[198:201], v153 offset:19456
	ds_read_b128 v[226:229], v153 offset:20480
	ds_read_b128 v[230:233], v153 offset:21504
	ds_read_b128 v[234:237], v153 offset:22528
	ds_read_b128 v[238:241], v153 offset:23552
	global_load_lds_dwordx4 v[202:203], off
	s_add_i32 m0, s41, 0x2000
	s_add_u32 s42, s18, 0x40000
	v_lshl_add_u64 v[208:209], s[18:19], 0, v[36:37]
	s_addc_u32 s43, s19, 0
	s_add_i32 s41, s44, s24
	global_load_lds_dwordx4 v[208:209], off
	s_mov_b32 m0, s41
	v_lshl_add_u64 v[218:219], s[20:21], 0, v[138:139]
	global_load_lds_dwordx4 v34, s[42:43]
	s_add_i32 m0, s41, 0x2000
	s_nop 0
	global_load_lds_dwordx4 v36, s[42:43]
	v_lshl_add_u64 v[210:211], s[20:21], 0, v[140:141]
	s_mov_b32 m0, s25
	s_nop 0
	global_load_lds_dwordx4 v[210:211], off
	s_mov_b32 m0, s26
	s_nop 0
	global_load_lds_dwordx4 v[218:219], off
	s_waitcnt vmcnt(8)
	s_waitcnt lgkmcnt(0)
	s_barrier
	s_setprio 1
	s_waitcnt lgkmcnt(0)
	v_mfma_f32_16x16x32_bf16 v[70:73], v[146:149], v[186:189], v[70:73]
	v_mfma_f32_16x16x32_bf16 v[66:69], v[158:161], v[186:189], v[66:69]
	v_mfma_f32_16x16x32_bf16 v[62:65], v[146:149], v[194:197], v[62:65]
	v_mfma_f32_16x16x32_bf16 v[54:57], v[158:161], v[194:197], v[54:57]
	v_mfma_f32_16x16x32_bf16 v[46:49], v[146:149], v[226:229], v[46:49]
	v_mfma_f32_16x16x32_bf16 v[30:33], v[158:161], v[226:229], v[30:33]
	v_mfma_f32_16x16x32_bf16 v[22:25], v[146:149], v[234:237], v[22:25]
	v_mfma_f32_16x16x32_bf16 v[14:17], v[158:161], v[234:237], v[14:17]
	v_mfma_f32_16x16x32_bf16 v[70:73], v[154:157], v[190:193], v[70:73]
	v_mfma_f32_16x16x32_bf16 v[66:69], v[162:165], v[190:193], v[66:69]
	v_mfma_f32_16x16x32_bf16 v[62:65], v[154:157], v[198:201], v[62:65]
	v_mfma_f32_16x16x32_bf16 v[54:57], v[162:165], v[198:201], v[54:57]
	v_mfma_f32_16x16x32_bf16 v[46:49], v[154:157], v[230:233], v[46:49]
	v_mfma_f32_16x16x32_bf16 v[30:33], v[162:165], v[230:233], v[30:33]
	v_mfma_f32_16x16x32_bf16 v[22:25], v[154:157], v[238:241], v[22:25]
	v_mfma_f32_16x16x32_bf16 v[14:17], v[162:165], v[238:241], v[14:17]
	s_setprio 0
	s_setprio 1
	v_mfma_f32_16x16x32_bf16 v[58:61], v[166:169], v[186:189], v[58:61]
	v_mfma_f32_16x16x32_bf16 v[50:53], v[174:177], v[186:189], v[50:53]
	v_mfma_f32_16x16x32_bf16 v[42:45], v[166:169], v[194:197], v[42:45]
	v_mfma_f32_16x16x32_bf16 v[26:29], v[174:177], v[194:197], v[26:29]
	v_mfma_f32_16x16x32_bf16 v[18:21], v[166:169], v[226:229], v[18:21]
	v_mfma_f32_16x16x32_bf16 v[10:13], v[174:177], v[226:229], v[10:13]
	v_mfma_f32_16x16x32_bf16 v[6:9], v[166:169], v[234:237], v[6:9]
	v_mfma_f32_16x16x32_bf16 v[2:5], v[174:177], v[234:237], v[2:5]
	v_mfma_f32_16x16x32_bf16 v[58:61], v[170:173], v[190:193], v[58:61]
	v_mfma_f32_16x16x32_bf16 v[50:53], v[178:181], v[190:193], v[50:53]
	v_mfma_f32_16x16x32_bf16 v[42:45], v[170:173], v[198:201], v[42:45]
	v_mfma_f32_16x16x32_bf16 v[26:29], v[178:181], v[198:201], v[26:29]
	v_mfma_f32_16x16x32_bf16 v[18:21], v[170:173], v[230:233], v[18:21]
	v_mfma_f32_16x16x32_bf16 v[10:13], v[178:181], v[230:233], v[10:13]
	v_mfma_f32_16x16x32_bf16 v[6:9], v[170:173], v[238:241], v[6:9]
	v_mfma_f32_16x16x32_bf16 v[2:5], v[178:181], v[238:241], v[2:5]
	s_setprio 0
	s_barrier
; #define PG8_STAGE(bufoff, gbase, voff) do { _Pragma("unroll") for (int _i = 0; _i < 2; ++_i) \
;         __builtin_amdgcn_global_load_lds((const unsigned*)((const char*)(gbase) + (voff)[_i]), (PG8_LAS unsigned*)(lds + (bufoff) + ldsw + _i * 8192), 16, 0, 0); } while (0)
; #define PG8_LDA(dst, b, h) do { _Pragma("unroll") for (int m = 0; m < 4; ++m) _Pragma("unroll") for (int k = 0; k < 2; ++k) dst[m][k] = *(const PG8_LAS bf16x8*)(lds + PG8_SA(b, h) + aoff + m * 2048 + k * 1024); } while (0)
; #define PG8_LDB(dst, b, h) do { _Pragma("unroll") for (int n = 0; n < 2; ++n) _Pragma("unroll") for (int k = 0; k < 2; ++k) dst[n][k] = *(const PG8_LAS bf16x8*)(lds + PG8_SB(b, h) + boff + n * 2048 + k * 1024); } while (0)
; #define PG8_MMA(ai, bj, At, Bt) do { __builtin_amdgcn_s_setprio(1); _Pragma("unroll") for (int m = 0; m < 4; ++m) _Pragma("unroll") for (int n = 0; n < 2; ++n) _Pragma("unroll") for (int k = 0; k < 2; ++k) \
;         acc[ai][bj][m][n] = __builtin_amdgcn_mfma_f32_16x16x32_bf16(Bt[n][k], At[m][k], acc[ai][bj][m][n], 0, 0, 0); __builtin_amdgcn_s_setprio(0); } while (0)
; #define PG8_WAIT_V(n) asm volatile("s_waitcnt vmcnt(" #n ")" ::: "memory")
; #define PG8_WAIT_L(n) asm volatile("s_waitcnt lgkmcnt(" #n ")" ::: "memory")
; #define PG8_BAR __builtin_amdgcn_s_barrier()
; #define PG8_SCHED __builtin_amdgcn_sched_barrier(0)
; template <class Epi, class Sched, bool ALIGN_EPI = false, bool SP2 = false>
; __device__ __forceinline__ void gemm_phase(PG8_LAS unsigned char* lds, const Gemm g, const Sched& S, const Epi& E) {
;     ...
;             PG8_LDB(B0, 1, 0); PG8_LDB(B1, 1, 1); PG8_SCHED; PG8_LDA(At, 1, 0); PG8_STAGE(PG8_SA(0, 1), a2 + hstep, voffA);
;             PG8_WAIT_V(8); PG8_WAIT_L(0); PG8_BAR; PG8_MMA(0, 0, At, B0); PG8_MMA(0, 1, At, B1); PG8_BAR; PG8_SCHED;
	s_add_i32 s41, 0, 0x18000
	v_add_u32_e32 v38, s41, v151
	s_add_i32 s42, 0, 0x1c000
	ds_read_b128 v[146:149], v38
	ds_read_b128 v[154:157], v38 offset:1024
	ds_read_b128 v[158:161], v38 offset:2048
	ds_read_b128 v[162:165], v38 offset:3072
	v_add_u32_e32 v38, s42, v151
	ds_read_b128 v[166:169], v38
	ds_read_b128 v[170:173], v38 offset:1024
	ds_read_b128 v[174:177], v38 offset:2048
	ds_read_b128 v[178:181], v38 offset:3072
	s_add_u32 s20, s20, 0x40000
	s_addc_u32 s21, s21, 0
	s_mov_b32 m0, s27
	ds_read_b128 v[186:189], v153 offset:32768
	ds_read_b128 v[190:193], v153 offset:33792
	ds_read_b128 v[194:197], v153 offset:34816
	ds_read_b128 v[198:201], v153 offset:35840
	ds_read_b128 v[226:229], v153 offset:36864
	ds_read_b128 v[230:233], v153 offset:37888
	ds_read_b128 v[234:237], v153 offset:38912
	ds_read_b128 v[238:241], v153 offset:39936
	global_load_lds_dwordx4 v140, s[20:21]
	v_lshl_add_u64 v[220:221], s[20:21], 0, v[138:139]
	s_mov_b32 m0, s28
	s_nop 0
	global_load_lds_dwordx4 v[220:221], off
	s_waitcnt vmcnt(8)
	s_waitcnt lgkmcnt(0)
	s_barrier
	s_setprio 1
	s_waitcnt lgkmcnt(0)
	v_mfma_f32_16x16x32_bf16 v[134:137], v[146:149], v[186:189], v[134:137]
	v_mfma_f32_16x16x32_bf16 v[130:133], v[158:161], v[186:189], v[130:133]
	v_mfma_f32_16x16x32_bf16 v[126:129], v[146:149], v[194:197], v[126:129]
	v_mfma_f32_16x16x32_bf16 v[118:121], v[158:161], v[194:197], v[118:121]
	v_mfma_f32_16x16x32_bf16 v[110:113], v[146:149], v[226:229], v[110:113]
	v_mfma_f32_16x16x32_bf16 v[102:105], v[158:161], v[226:229], v[102:105]
	v_mfma_f32_16x16x32_bf16 v[94:97], v[146:149], v[234:237], v[94:97]
	v_mfma_f32_16x16x32_bf16 v[86:89], v[158:161], v[234:237], v[86:89]
	v_mfma_f32_16x16x32_bf16 v[134:137], v[154:157], v[190:193], v[134:137]
	v_mfma_f32_16x16x32_bf16 v[130:133], v[162:165], v[190:193], v[130:133]
	v_mfma_f32_16x16x32_bf16 v[126:129], v[154:157], v[198:201], v[126:129]
	v_mfma_f32_16x16x32_bf16 v[118:121], v[162:165], v[198:201], v[118:121]
	v_mfma_f32_16x16x32_bf16 v[110:113], v[154:157], v[230:233], v[110:113]
	v_mfma_f32_16x16x32_bf16 v[102:105], v[162:165], v[230:233], v[102:105]
	v_mfma_f32_16x16x32_bf16 v[94:97], v[154:157], v[238:241], v[94:97]
	v_mfma_f32_16x16x32_bf16 v[86:89], v[162:165], v[238:241], v[86:89]
	s_setprio 0
	s_setprio 1
	v_mfma_f32_16x16x32_bf16 v[122:125], v[166:169], v[186:189], v[122:125]
	v_mfma_f32_16x16x32_bf16 v[114:117], v[174:177], v[186:189], v[114:117]
	v_mfma_f32_16x16x32_bf16 v[106:109], v[166:169], v[194:197], v[106:109]
	v_mfma_f32_16x16x32_bf16 v[98:101], v[174:177], v[194:197], v[98:101]
	v_mfma_f32_16x16x32_bf16 v[90:93], v[166:169], v[226:229], v[90:93]
	v_mfma_f32_16x16x32_bf16 v[82:85], v[174:177], v[226:229], v[82:85]
	v_mfma_f32_16x16x32_bf16 v[78:81], v[166:169], v[234:237], v[78:81]
	v_mfma_f32_16x16x32_bf16 v[74:77], v[174:177], v[234:237], v[74:77]
	v_mfma_f32_16x16x32_bf16 v[122:125], v[170:173], v[190:193], v[122:125]
	v_mfma_f32_16x16x32_bf16 v[114:117], v[178:181], v[190:193], v[114:117]
	v_mfma_f32_16x16x32_bf16 v[106:109], v[170:173], v[198:201], v[106:109]
	v_mfma_f32_16x16x32_bf16 v[98:101], v[178:181], v[198:201], v[98:101]
	v_mfma_f32_16x16x32_bf16 v[90:93], v[170:173], v[230:233], v[90:93]
	v_mfma_f32_16x16x32_bf16 v[82:85], v[178:181], v[230:233], v[82:85]
	v_mfma_f32_16x16x32_bf16 v[78:81], v[170:173], v[238:241], v[78:81]
	v_mfma_f32_16x16x32_bf16 v[74:77], v[178:181], v[238:241], v[74:77]
	s_setprio 0
	s_barrier
; #define PG8_STAGE(bufoff, gbase, voff) do { _Pragma("unroll") for (int _i = 0; _i < 2; ++_i) \
;         __builtin_amdgcn_global_load_lds((const unsigned*)((const char*)(gbase) + (voff)[_i]), (PG8_LAS unsigned*)(lds + (bufoff) + ldsw + _i * 8192), 16, 0, 0); } while (0)
; #define PG8_LDA(dst, b, h) do { _Pragma("unroll") for (int m = 0; m < 4; ++m) _Pragma("unroll") for (int k = 0; k < 2; ++k) dst[m][k] = *(const PG8_LAS bf16x8*)(lds + PG8_SA(b, h) + aoff + m * 2048 + k * 1024); } while (0)
; #define PG8_MMA(ai, bj, At, Bt) do { __builtin_amdgcn_s_setprio(1); _Pragma("unroll") for (int m = 0; m < 4; ++m) _Pragma("unroll") for (int n = 0; n < 2; ++n) _Pragma("unroll") for (int k = 0; k < 2; ++k) \
;         acc[ai][bj][m][n] = __builtin_amdgcn_mfma_f32_16x16x32_bf16(Bt[n][k], At[m][k], acc[ai][bj][m][n], 0, 0, 0); __builtin_amdgcn_s_setprio(0); } while (0)
; #define PG8_WAIT_V(n) asm volatile("s_waitcnt vmcnt(" #n ")" ::: "memory")
; #define PG8_WAIT_L(n) asm volatile("s_waitcnt lgkmcnt(" #n ")" ::: "memory")
; #define PG8_BAR __builtin_amdgcn_s_barrier()
; #define PG8_SCHED __builtin_amdgcn_sched_barrier(0)
; template <class Epi, class Sched, bool ALIGN_EPI = false, bool SP2 = false>
; __device__ __forceinline__ void gemm_phase(PG8_LAS unsigned char* lds, const Gemm g, const Sched& S, const Epi& E) {
;     ...
;             PG8_LDA(At, 1, 1); PG8_STAGE(PG8_SB(1, 0), b3, voffB); PG8_STAGE(PG8_SB(1, 1), b3 + hstep, voffB); PG8_STAGE(PG8_SA(1, 0), a3, voffA);
;             PG8_WAIT_V(8); PG8_WAIT_L(0); PG8_BAR; PG8_MMA(1, 0, At, B0); PG8_MMA(1, 1, At, B1); PG8_BAR; PG8_SCHED;
;     ...
;         }
;         if constexpr (ALIGN_EPI) { if (wr == 0) PG8_BAR; }
	s_add_i32 s20, s41, s24
	v_lshl_add_u64 v[202:203], v[202:203], 0, s[70:71]
	s_mov_b32 m0, s20
	ds_read_b128 v[186:189], v153 offset:49152
	ds_read_b128 v[190:193], v153 offset:50176
	ds_read_b128 v[194:197], v153 offset:51200
	ds_read_b128 v[198:201], v153 offset:52224
	ds_read_b128 v[226:229], v153 offset:53248
	ds_read_b128 v[230:233], v153 offset:54272
	ds_read_b128 v[234:237], v153 offset:55296
	ds_read_b128 v[238:241], v153 offset:56320
	global_load_lds_dwordx4 v[202:203], off
	s_add_i32 m0, s20, 0x2000
	s_add_u32 s18, s18, 0x40080
	v_lshl_add_u64 v[202:203], v[208:209], 0, s[70:71]
	s_addc_u32 s19, s19, 0
	s_add_i32 s20, s42, s24
	global_load_lds_dwordx4 v[202:203], off
	s_mov_b32 m0, s20
	s_nop 0
	global_load_lds_dwordx4 v34, s[18:19]
	s_add_i32 m0, s20, 0x2000
	s_nop 0
	global_load_lds_dwordx4 v36, s[18:19]
	v_lshl_add_u64 v[202:203], v[210:211], 0, s[70:71]
	s_mov_b32 m0, s29
	s_nop 0
	global_load_lds_dwordx4 v[202:203], off
	v_lshl_add_u64 v[202:203], v[218:219], 0, s[70:71]
	s_mov_b32 m0, s30
	s_nop 0
	global_load_lds_dwordx4 v[202:203], off
	s_waitcnt vmcnt(8)
	s_waitcnt lgkmcnt(0)
	s_barrier
	s_setprio 1
	s_waitcnt lgkmcnt(0)
	v_mfma_f32_16x16x32_bf16 v[70:73], v[146:149], v[186:189], v[70:73]
	v_mfma_f32_16x16x32_bf16 v[66:69], v[158:161], v[186:189], v[66:69]
	v_mfma_f32_16x16x32_bf16 v[62:65], v[146:149], v[194:197], v[62:65]
	v_mfma_f32_16x16x32_bf16 v[54:57], v[158:161], v[194:197], v[54:57]
	v_mfma_f32_16x16x32_bf16 v[46:49], v[146:149], v[226:229], v[46:49]
	v_mfma_f32_16x16x32_bf16 v[30:33], v[158:161], v[226:229], v[30:33]
	v_mfma_f32_16x16x32_bf16 v[22:25], v[146:149], v[234:237], v[22:25]
	v_mfma_f32_16x16x32_bf16 v[14:17], v[158:161], v[234:237], v[14:17]
	v_mfma_f32_16x16x32_bf16 v[70:73], v[154:157], v[190:193], v[70:73]
	v_mfma_f32_16x16x32_bf16 v[66:69], v[162:165], v[190:193], v[66:69]
	v_mfma_f32_16x16x32_bf16 v[62:65], v[154:157], v[198:201], v[62:65]
	v_mfma_f32_16x16x32_bf16 v[54:57], v[162:165], v[198:201], v[54:57]
	v_mfma_f32_16x16x32_bf16 v[46:49], v[154:157], v[230:233], v[46:49]
	v_mfma_f32_16x16x32_bf16 v[30:33], v[162:165], v[230:233], v[30:33]
	v_mfma_f32_16x16x32_bf16 v[22:25], v[154:157], v[238:241], v[22:25]
	v_mfma_f32_16x16x32_bf16 v[14:17], v[162:165], v[238:241], v[14:17]
	s_setprio 0
	s_setprio 1
	v_mfma_f32_16x16x32_bf16 v[58:61], v[166:169], v[186:189], v[58:61]
	v_mfma_f32_16x16x32_bf16 v[50:53], v[174:177], v[186:189], v[50:53]
	v_mfma_f32_16x16x32_bf16 v[42:45], v[166:169], v[194:197], v[42:45]
	v_mfma_f32_16x16x32_bf16 v[26:29], v[174:177], v[194:197], v[26:29]
	v_mfma_f32_16x16x32_bf16 v[18:21], v[166:169], v[226:229], v[18:21]
	v_mfma_f32_16x16x32_bf16 v[10:13], v[174:177], v[226:229], v[10:13]
	v_mfma_f32_16x16x32_bf16 v[6:9], v[166:169], v[234:237], v[6:9]
	v_mfma_f32_16x16x32_bf16 v[2:5], v[174:177], v[234:237], v[2:5]
	v_mfma_f32_16x16x32_bf16 v[58:61], v[170:173], v[190:193], v[58:61]
	v_mfma_f32_16x16x32_bf16 v[50:53], v[178:181], v[190:193], v[50:53]
	v_mfma_f32_16x16x32_bf16 v[42:45], v[170:173], v[198:201], v[42:45]
	v_mfma_f32_16x16x32_bf16 v[26:29], v[178:181], v[198:201], v[26:29]
	v_mfma_f32_16x16x32_bf16 v[18:21], v[170:173], v[230:233], v[18:21]
	v_mfma_f32_16x16x32_bf16 v[10:13], v[178:181], v[230:233], v[10:13]
	v_mfma_f32_16x16x32_bf16 v[6:9], v[170:173], v[238:241], v[6:9]
	v_mfma_f32_16x16x32_bf16 v[2:5], v[178:181], v[238:241], v[2:5]
	s_setprio 0
	s_barrier
	s_add_i32 s40, s40, 2
	s_add_u32 s16, s16, 0x100
	s_addc_u32 s17, s17, 0
	s_add_u32 s38, s38, 0x100
	s_addc_u32 s39, s39, 0
	s_cmp_gt_u32 s40, 13
	s_cbranch_scc0 .LBB0_185
	s_and_b64 vcc, exec, s[4:5]
	s_cbranch_vccz .LBB0_188
	s_barrier

; #define PG8_STAGE(bufoff, gbase, voff) do { _Pragma("unroll") for (int _i = 0; _i < 2; ++_i) \
;         __builtin_amdgcn_global_load_lds((const unsigned*)((const char*)(gbase) + (voff)[_i]), (PG8_LAS unsigned*)(lds + (bufoff) + ldsw + _i * 8192), 16, 0, 0); } while (0)
; #define PG8_WAIT_V(n) asm volatile("s_waitcnt vmcnt(" #n ")" ::: "memory")
; #define PG8_BAR __builtin_amdgcn_s_barrier()
;     __device__ __forceinline__ void operator()(const f32x4 (&acc)[2][2][4][2], const Unit& u, int wr, int wc, int fr, int fq) const {
;         int seqrow, tstart, T, vlo, vhi;
;         if (u.pm < 132) { const int b = u.pm / 33, i = u.pm - b * 33; seqrow = b * 8192; tstart = 254 * i - 1; T = 8192; vlo = 1; vhi = 255; }
;         else { seqrow = 32768 + (u.pm - 132) * 256; tstart = 0; T = 256; vlo = 0; vhi = 256; }
;         const bool edge = (tstart <= 0) || (tstart + 256 >= T);
;         const int ch0 = 128 * u.pn + 32 * wc + 8 * fq;
; template <class Epi, class Sched, bool ALIGN_EPI = false, bool SP2 = false>
; __device__ __forceinline__ void gemm_phase(PG8_LAS unsigned char* lds, const Gemm g, const Sched& S, const Epi& E) {
;     ...
;         PG8_STAGE(PG8_SB(1, 0), cB + kstep, voffB); PG8_STAGE(PG8_SA(1, 0), cA + kstep, voffA); PG8_STAGE(PG8_SB(1, 1), cB + hstep + kstep, voffB);
;         PG8_WAIT_V(6); PG8_BAR;
.LBB0_685:
	v_readlane_b32 s0, v254, 27
	s_mov_b32 s16, s0
	s_mul_i32 s0, s0, 0x10800
	s_add_u32 s62, s8, s0
	s_addc_u32 s63, s7, 0
	s_mul_i32 s0, s16, 0x5800
	s_add_u32 s64, s14, s0
	s_addc_u32 s65, s9, 0
	s_add_u32 s66, s62, 0x5800
	s_addc_u32 s67, s63, 0
	s_add_u32 s68, s62, 0xb000
	s_addc_u32 s69, s63, 0
	s_and_b32 s3, s4, 3
	s_add_i32 m0, s80, 0x18000
	v_lshl_add_u64 v[6:7], v[6:7], 0, s[70:71]
	s_lshl_b32 s4, s15, 13
	s_lshl_b32 s5, s3, 12
	s_waitcnt vmcnt(2)
	s_barrier
	global_load_lds_dwordx4 v[6:7], off
	v_lshl_add_u64 v[4:5], v[4:5], 0, s[70:71]
	s_add_i32 m0, s80, 0x1a000
	s_add_i32 s82, s80, 0x8000
	s_add_i32 s83, s80, 0xa000
	v_readlane_b32 s1, v254, 28
	global_load_lds_dwordx4 v[4:5], off
	v_lshl_add_u64 v[2:3], v[2:3], 0, s[70:71]
	s_mov_b32 m0, s82
	s_add_u32 s0, s10, 0x40080
	global_load_lds_dwordx4 v[2:3], off
	v_lshl_add_u64 v[2:3], v[8:9], 0, s[70:71]
	s_mov_b32 m0, s83
	s_addc_u32 s1, s11, 0
	global_load_lds_dwordx4 v[2:3], off
	s_add_i32 m0, s80, 0x1c000
	s_nop 0
	global_load_lds_dwordx4 v34, s[0:1]
	v_lshl_add_u64 v[2:3], s[0:1], 0, v[188:189]
	s_add_i32 m0, s80, 0x1e000
	v_readlane_b32 s0, v255, 5
	global_load_lds_dwordx4 v[2:3], off
	v_readlane_b32 s1, v255, 6
	s_mov_b32 s1, s79
	v_writelane_b32 v255, s0, 5
	s_cmpk_lt_u32 s6, 0x100
	v_bfe_u32 v2, v10, 4, 2
	v_writelane_b32 v255, s1, 6
	s_cselect_b64 s[0:1], -1, 0
	v_writelane_b32 v255, s0, 13
	v_and_b32_e32 v226, 15, v10
	v_lshlrev_b32_e32 v3, 3, v2
	v_writelane_b32 v255, s1, 14
	s_lshl_b32 s0, s3, 2
	s_lshl_b32 s1, s15, 5
	v_lshlrev_b32_e32 v4, 4, v2
	v_lshlrev_b32_e32 v5, 2, v10
	s_or_b32 s1, s0, s1
	v_lshl_or_b32 v4, v226, 6, v4
	v_and_b32_e32 v5, 32, v5
	v_lshl_or_b32 v229, s3, 5, v3
	v_or_b32_e32 v3, s1, v2
	s_add_i32 s1, s15, 2
	v_bitop3_b32 v6, v4, s4, v5 bitop3:0xde
	s_lshl_b32 s4, s1, 5
	s_or_b32 s0, s0, s4
	s_cmp_gt_i32 s15, 0
	v_bitop3_b32 v228, v4, s5, v5 bitop3:0xde
	v_or_b32_e32 v4, s0, v2
	s_cselect_b64 s[74:75], -1, 0
	s_lshl_b32 s0, s15, 11
	s_lshl_b32 s3, s3, 8
	s_cmp_lt_i32 s15, 3
	s_cselect_b64 s[8:9], -1, 0
	v_writelane_b32 v255, s8, 15
	s_cmp_gt_i32 s15, -2
	v_lshlrev_b32_e32 v230, 6, v2
	v_writelane_b32 v255, s9, 16
	s_cselect_b64 s[8:9], -1, 0
	s_lshl_b32 s1, s1, 11
	v_writelane_b32 v255, s8, 1
	s_cmp_lt_i32 s15, 1
	v_lshlrev_b32_e32 v2, 14, v11
	v_writelane_b32 v255, s9, 2
	s_cselect_b64 s[8:9], -1, 0
	v_writelane_b32 v255, s8, 17
	v_and_b32_e32 v2, 0xffff8000, v2
	v_lshl_add_u32 v2, v12, 11, v2
	v_writelane_b32 v255, s9, 18
	v_readlane_b32 s8, v254, 26
	s_add_i32 s0, s8, s0
	s_add_i32 s0, s0, s3
	v_lshl_add_u32 v238, v3, 6, s8
	v_and_b32_e32 v3, 1, v11
	v_lshl_or_b32 v2, v3, 6, v2
	v_lshl_add_u32 v190, v13, 1, v2
	v_lshlrev_b32_e32 v2, 14, v14
	s_add_i32 s9, s0, 0xfffffc00
	v_add_u32_e32 v240, s0, v230
	s_add_i32 s0, s8, s1
	v_and_b32_e32 v2, 0xffff8000, v2
	s_waitcnt vmcnt(6)
	s_add_i32 s0, s0, s3
	v_lshl_add_u32 v2, v15, 11, v2
	v_and_b32_e32 v3, 1, v14
	v_lshl_or_b32 v227, s15, 6, v226
	v_writelane_b32 v255, s9, 25
	s_add_i32 s1, s0, 0xfffffc00
	v_lshl_or_b32 v2, v3, 6, v2
	v_cmp_eq_u32_e64 s[4:5], 15, v226
	s_mov_b32 s90, 0
	v_cmp_eq_u32_e64 s[6:7], 0, v226
	v_or_b32_e32 v231, 16, v227
	v_or_b32_e32 v232, 32, v227
	v_or_b32_e32 v233, 48, v227
	v_add_u32_e32 v234, 0x80, v227
	v_add_u32_e32 v235, 0x90, v227
	v_add_u32_e32 v236, 0xa0, v227
	v_add_u32_e32 v237, 0xb0, v227
	v_lshl_add_u32 v239, v4, 6, s8
	v_writelane_b32 v255, s1, 26
	v_add_u32_e32 v241, s0, v230
	v_mov_b32_e32 v191, v35
	v_lshl_add_u32 v192, v16, 1, v2
	v_mov_b32_e32 v193, v35
	v_add_u32_e32 v242, 0, v6
	s_barrier
	s_branch .LBB0_688

;     __device__ __forceinline__ long arow(int pm) const { return (long)pm * BM; }
;     __device__ __forceinline__ long arow(int pm) const { if (pm < 132) { const int b = pm / 33, i = pm - b * 33; return (long)b * 8192 + 254 * i - 1; } return 32768 + (long)(pm - 132) * 256; }
;     __device__ __forceinline__ bool next(int i, Unit& u) const { if (i > 0) return false; u.pm = pm; u.pn = pn; return true; }
;     __device__ __forceinline__ long arow(int p) const { return (long)p * BM; }
; #define PG8_STAGE(bufoff, gbase, voff) do { _Pragma("unroll") for (int _i = 0; _i < 2; ++_i) \
;         __builtin_amdgcn_global_load_lds((const unsigned*)((const char*)(gbase) + (voff)[_i]), (PG8_LAS unsigned*)(lds + (bufoff) + ldsw + _i * 8192), 16, 0, 0); } while (0)
; #define PG8_LDA(dst, b, h) do { _Pragma("unroll") for (int m = 0; m < 4; ++m) _Pragma("unroll") for (int k = 0; k < 2; ++k) dst[m][k] = *(const PG8_LAS bf16x8*)(lds + PG8_SA(b, h) + aoff + m * 2048 + k * 1024); } while (0)
; template <class Epi, class Sched, bool ALIGN_EPI = false, bool SP2 = false>
; __device__ __forceinline__ void gemm_phase(PG8_LAS unsigned char* lds, const Gemm g, const Sched& S, const Epi& E) {
;     ...
;         const bool has_next = S.next(ui + 1, nxt);
;         const char* nA = has_next ? (const char*)g.A + S.arow(nxt.pm) * rowb : cA; const char* nB = has_next ? (const char*)g.Bt + (size_t)nxt.pn * tstep : cB;
;         for (int t = 0; t < nt; t += 2) {
;             const bool last = (t == nt - 2);
;             const char* a1 = cA + (size_t)(t + 1) * kstep;
;             const char* a2 = last ? nA : cA + (size_t)(t + 2) * kstep; const char* b2 = last ? nB : cB + (size_t)(t + 2) * kstep;
;             const char* a3 = a2 + kstep; const char* b3 = b2 + kstep;
;             if (last && has_next) S.a_ready(nxt);
;             if constexpr (SP2) {
;             PG8_LDB(B0, 0, 0); PG8_LDB(B1, 0, 1); PG8_SCHED; PG8_LDA(At, 0, 0); PG8_STAGE(PG8_SA(1, 1), a1 + hstep, voffA);
;             PG8_WAIT_V(8); PG8_WAIT_L(0); PG8_BAR; PG8_MMA(0, 0, At, B0); PG8_MMA(0, 1, At, B1); PG8_BAR; PG8_SCHED;
;             PG8_LDA(At, 0, 1); PG8_STAGE(PG8_SB(0, 0), b2, voffB); PG8_STAGE(PG8_SB(0, 1), b2 + hstep, voffB); PG8_STAGE(PG8_SA(0, 0), a2, voffA);
;             PG8_WAIT_V(8); PG8_WAIT_L(0); PG8_BAR; PG8_MMA(1, 0, At, B0); PG8_MMA(1, 1, At, B1); PG8_BAR; PG8_SCHED;
.LBB0_696:
	s_ashr_i32 s93, s92, 31
	s_lshl_b64 s[14:15], s[92:93], 19
	v_readlane_b32 s3, v255, 9
	s_add_u32 s96, s3, s14
	v_readlane_b32 s3, v255, 11
	s_addc_u32 s97, s3, s15
	s_and_b64 s[0:1], s[0:1], exec
	s_cselect_b32 s3, s97, s11
	s_cselect_b32 s14, s96, s10
	s_add_u32 s0, s12, 0x40080
	s_addc_u32 s1, s13, 0
	s_add_u32 s15, s10, 0x100
	s_addc_u32 s16, s11, 0
	s_mov_b32 s17, -2
	s_waitcnt vmcnt(0)
	s_add_u32 s10, s0, 0xfffc0080
	s_addc_u32 s11, s1, -1
	s_add_i32 s19, 0, 0x10000
	s_cmp_eq_u32 s17, 12
	s_cselect_b32 s13, s95, s11
	s_cselect_b32 s12, s94, s10
	v_add_u32_e32 v38, s19, v228
	s_cselect_b32 s11, s3, s16
	s_cselect_b32 s10, s14, s15
	s_add_i32 s22, 0, 0x14000
	ds_read_b128 v[106:109], v38
	ds_read_b128 v[110:113], v38 offset:1024
	ds_read_b128 v[114:117], v38 offset:2048
	ds_read_b128 v[118:121], v38 offset:3072
	v_add_u32_e32 v38, s22, v228
	ds_read_b128 v[122:125], v38
	ds_read_b128 v[126:129], v38 offset:1024
	ds_read_b128 v[130:133], v38 offset:2048
	ds_read_b128 v[134:137], v38 offset:3072
	s_add_i32 m0, s80, 0xc000
	ds_read_b128 v[170:173], v242
	ds_read_b128 v[174:177], v242 offset:1024
	ds_read_b128 v[178:181], v242 offset:2048
	ds_read_b128 v[194:197], v242 offset:3072
	ds_read_b128 v[198:201], v242 offset:4096
	ds_read_b128 v[208:211], v242 offset:5120
	ds_read_b128 v[218:221], v242 offset:6144
	ds_read_b128 v[244:247], v242 offset:7168
	global_load_lds_dwordx4 v190, s[0:1]
	s_add_i32 m0, s80, 0xe000
	s_nop 0
	global_load_lds_dwordx4 v192, s[0:1]
	s_waitcnt vmcnt(8)
	s_waitcnt lgkmcnt(0)
	s_barrier
	s_setprio 1
	s_waitcnt lgkmcnt(0)
	v_mfma_f32_16x16x32_bf16 v[166:169], v[106:109], v[170:173], 0
	v_mfma_f32_16x16x32_bf16 v[70:73], v[114:117], v[170:173], 0
	v_mfma_f32_16x16x32_bf16 v[158:161], v[106:109], v[178:181], 0
	v_mfma_f32_16x16x32_bf16 v[62:65], v[114:117], v[178:181], 0
	v_mfma_f32_16x16x32_bf16 v[150:153], v[106:109], v[198:201], 0
	v_mfma_f32_16x16x32_bf16 v[54:57], v[114:117], v[198:201], 0
	v_mfma_f32_16x16x32_bf16 v[142:145], v[106:109], v[218:221], 0
	v_mfma_f32_16x16x32_bf16 v[46:49], v[114:117], v[218:221], 0
	v_mfma_f32_16x16x32_bf16 v[166:169], v[110:113], v[174:177], v[166:169]
	v_mfma_f32_16x16x32_bf16 v[70:73], v[118:121], v[174:177], v[70:73]
	v_mfma_f32_16x16x32_bf16 v[158:161], v[110:113], v[194:197], v[158:161]
	v_mfma_f32_16x16x32_bf16 v[62:65], v[118:121], v[194:197], v[62:65]
	v_mfma_f32_16x16x32_bf16 v[150:153], v[110:113], v[208:211], v[150:153]
	v_mfma_f32_16x16x32_bf16 v[54:57], v[118:121], v[208:211], v[54:57]
	v_mfma_f32_16x16x32_bf16 v[142:145], v[110:113], v[244:247], v[142:145]
	v_mfma_f32_16x16x32_bf16 v[46:49], v[118:121], v[244:247], v[46:49]
	s_setprio 0
	s_setprio 1
	v_mfma_f32_16x16x32_bf16 v[162:165], v[122:125], v[170:173], 0
	v_mfma_f32_16x16x32_bf16 v[66:69], v[130:133], v[170:173], 0
	v_mfma_f32_16x16x32_bf16 v[154:157], v[122:125], v[178:181], 0
	v_mfma_f32_16x16x32_bf16 v[58:61], v[130:133], v[178:181], 0
	v_mfma_f32_16x16x32_bf16 v[146:149], v[122:125], v[198:201], 0
	v_mfma_f32_16x16x32_bf16 v[50:53], v[130:133], v[198:201], 0
	v_mfma_f32_16x16x32_bf16 v[138:141], v[122:125], v[218:221], 0
	v_mfma_f32_16x16x32_bf16 v[42:45], v[130:133], v[218:221], 0
	v_mfma_f32_16x16x32_bf16 v[162:165], v[126:129], v[174:177], v[162:165]
	v_mfma_f32_16x16x32_bf16 v[66:69], v[134:137], v[174:177], v[66:69]
	v_mfma_f32_16x16x32_bf16 v[154:157], v[126:129], v[194:197], v[154:157]
	v_mfma_f32_16x16x32_bf16 v[58:61], v[134:137], v[194:197], v[58:61]
	v_mfma_f32_16x16x32_bf16 v[146:149], v[126:129], v[208:211], v[146:149]
	v_mfma_f32_16x16x32_bf16 v[50:53], v[134:137], v[208:211], v[50:53]
	v_mfma_f32_16x16x32_bf16 v[138:141], v[126:129], v[244:247], v[138:141]
	v_mfma_f32_16x16x32_bf16 v[42:45], v[134:137], v[244:247], v[42:45]
	s_setprio 0
	s_barrier
	s_add_i32 s19, s19, s59
	v_lshl_add_u64 v[202:203], s[10:11], 0, v[34:35]
	s_mov_b32 m0, s19
	ds_read_b128 v[170:173], v242 offset:16384
	ds_read_b128 v[174:177], v242 offset:17408
	ds_read_b128 v[178:181], v242 offset:18432
	ds_read_b128 v[194:197], v242 offset:19456
	ds_read_b128 v[198:201], v242 offset:20480
	ds_read_b128 v[208:211], v242 offset:21504
	ds_read_b128 v[218:221], v242 offset:22528
	ds_read_b128 v[244:247], v242 offset:23552
	global_load_lds_dwordx4 v[202:203], off
	s_add_i32 m0, s19, 0x2000
	s_add_u32 s20, s10, 0x40000
	v_lshl_add_u64 v[212:213], s[10:11], 0, v[188:189]
	s_addc_u32 s21, s11, 0
	s_add_i32 s19, s22, s59
	global_load_lds_dwordx4 v[212:213], off
	s_mov_b32 m0, s19
	v_lshl_add_u64 v[250:251], s[12:13], 0, v[186:187]
	global_load_lds_dwordx4 v34, s[20:21]
	s_add_i32 m0, s19, 0x2000
	s_nop 0
	global_load_lds_dwordx4 v188, s[20:21]
	v_lshl_add_u64 v[248:249], s[12:13], 0, v[36:37]
	s_mov_b32 m0, s80
	s_nop 0
	global_load_lds_dwordx4 v[248:249], off
	s_mov_b32 m0, s81
	s_nop 0
	global_load_lds_dwordx4 v[250:251], off
	s_waitcnt vmcnt(8)
	s_waitcnt lgkmcnt(0)
	s_barrier
; #define PG8_STAGE(bufoff, gbase, voff) do { _Pragma("unroll") for (int _i = 0; _i < 2; ++_i) \
;         __builtin_amdgcn_global_load_lds((const unsigned*)((const char*)(gbase) + (voff)[_i]), (PG8_LAS unsigned*)(lds + (bufoff) + ldsw + _i * 8192), 16, 0, 0); } while (0)
; #define PG8_LDA(dst, b, h) do { _Pragma("unroll") for (int m = 0; m < 4; ++m) _Pragma("unroll") for (int k = 0; k < 2; ++k) dst[m][k] = *(const PG8_LAS bf16x8*)(lds + PG8_SA(b, h) + aoff + m * 2048 + k * 1024); } while (0)
; #define PG8_LDB(dst, b, h) do { _Pragma("unroll") for (int n = 0; n < 2; ++n) _Pragma("unroll") for (int k = 0; k < 2; ++k) dst[n][k] = *(const PG8_LAS bf16x8*)(lds + PG8_SB(b, h) + boff + n * 2048 + k * 1024); } while (0)
; #define PG8_MMA(ai, bj, At, Bt) do { __builtin_amdgcn_s_setprio(1); _Pragma("unroll") for (int m = 0; m < 4; ++m) _Pragma("unroll") for (int n = 0; n < 2; ++n) _Pragma("unroll") for (int k = 0; k < 2; ++k) \
;         acc[ai][bj][m][n] = __builtin_amdgcn_mfma_f32_16x16x32_bf16(Bt[n][k], At[m][k], acc[ai][bj][m][n], 0, 0, 0); __builtin_amdgcn_s_setprio(0); } while (0)
; #define PG8_WAIT_V(n) asm volatile("s_waitcnt vmcnt(" #n ")" ::: "memory")
; #define PG8_WAIT_L(n) asm volatile("s_waitcnt lgkmcnt(" #n ")" ::: "memory")
; #define PG8_BAR __builtin_amdgcn_s_barrier()
; #define PG8_SCHED __builtin_amdgcn_sched_barrier(0)
; template <class Epi, class Sched, bool ALIGN_EPI = false, bool SP2 = false>
; __device__ __forceinline__ void gemm_phase(PG8_LAS unsigned char* lds, const Gemm g, const Sched& S, const Epi& E) {
;     ...
;             PG8_WAIT_V(8); PG8_WAIT_L(0); PG8_BAR; PG8_MMA(1, 0, At, B0); PG8_MMA(1, 1, At, B1); PG8_BAR; PG8_SCHED;
;             PG8_LDB(B0, 1, 0); PG8_LDB(B1, 1, 1); PG8_SCHED; PG8_LDA(At, 1, 0); PG8_STAGE(PG8_SA(0, 1), a2 + hstep, voffA);
;             PG8_WAIT_V(8); PG8_WAIT_L(0); PG8_BAR; PG8_MMA(0, 0, At, B0); PG8_MMA(0, 1, At, B1); PG8_BAR; PG8_SCHED;
	s_setprio 1
	s_waitcnt lgkmcnt(0)
	v_mfma_f32_16x16x32_bf16 v[102:105], v[106:109], v[170:173], 0
	v_mfma_f32_16x16x32_bf16 v[30:33], v[114:117], v[170:173], 0
	v_mfma_f32_16x16x32_bf16 v[94:97], v[106:109], v[178:181], 0
	v_mfma_f32_16x16x32_bf16 v[22:25], v[114:117], v[178:181], 0
	v_mfma_f32_16x16x32_bf16 v[86:89], v[106:109], v[198:201], 0
	v_mfma_f32_16x16x32_bf16 v[14:17], v[114:117], v[198:201], 0
	v_mfma_f32_16x16x32_bf16 v[78:81], v[106:109], v[218:221], 0
	v_mfma_f32_16x16x32_bf16 v[6:9], v[114:117], v[218:221], 0
	v_mfma_f32_16x16x32_bf16 v[102:105], v[110:113], v[174:177], v[102:105]
	v_mfma_f32_16x16x32_bf16 v[30:33], v[118:121], v[174:177], v[30:33]
	v_mfma_f32_16x16x32_bf16 v[94:97], v[110:113], v[194:197], v[94:97]
	v_mfma_f32_16x16x32_bf16 v[22:25], v[118:121], v[194:197], v[22:25]
	v_mfma_f32_16x16x32_bf16 v[86:89], v[110:113], v[208:211], v[86:89]
	v_mfma_f32_16x16x32_bf16 v[14:17], v[118:121], v[208:211], v[14:17]
	v_mfma_f32_16x16x32_bf16 v[78:81], v[110:113], v[244:247], v[78:81]
	v_mfma_f32_16x16x32_bf16 v[6:9], v[118:121], v[244:247], v[6:9]
	s_setprio 0
	s_setprio 1
	v_mfma_f32_16x16x32_bf16 v[98:101], v[122:125], v[170:173], 0
	v_mfma_f32_16x16x32_bf16 v[26:29], v[130:133], v[170:173], 0
	v_mfma_f32_16x16x32_bf16 v[90:93], v[122:125], v[178:181], 0
	v_mfma_f32_16x16x32_bf16 v[18:21], v[130:133], v[178:181], 0
	v_mfma_f32_16x16x32_bf16 v[82:85], v[122:125], v[198:201], 0
	v_mfma_f32_16x16x32_bf16 v[10:13], v[130:133], v[198:201], 0
	v_mfma_f32_16x16x32_bf16 v[74:77], v[122:125], v[218:221], 0
	v_mfma_f32_16x16x32_bf16 v[2:5], v[130:133], v[218:221], 0
	v_mfma_f32_16x16x32_bf16 v[98:101], v[126:129], v[174:177], v[98:101]
	v_mfma_f32_16x16x32_bf16 v[26:29], v[134:137], v[174:177], v[26:29]
	v_mfma_f32_16x16x32_bf16 v[90:93], v[126:129], v[194:197], v[90:93]
	v_mfma_f32_16x16x32_bf16 v[18:21], v[134:137], v[194:197], v[18:21]
	v_mfma_f32_16x16x32_bf16 v[82:85], v[126:129], v[208:211], v[82:85]
	v_mfma_f32_16x16x32_bf16 v[10:13], v[134:137], v[208:211], v[10:13]
	v_mfma_f32_16x16x32_bf16 v[74:77], v[126:129], v[244:247], v[74:77]
	v_mfma_f32_16x16x32_bf16 v[2:5], v[134:137], v[244:247], v[2:5]
	s_setprio 0
	s_barrier
	s_add_i32 s19, 0, 0x18000
	v_add_u32_e32 v38, s19, v228
	s_add_i32 s20, 0, 0x1c000
	ds_read_b128 v[106:109], v38
	ds_read_b128 v[110:113], v38 offset:1024
	ds_read_b128 v[114:117], v38 offset:2048
	ds_read_b128 v[118:121], v38 offset:3072
	v_add_u32_e32 v38, s20, v228
	ds_read_b128 v[122:125], v38
	ds_read_b128 v[126:129], v38 offset:1024
	ds_read_b128 v[130:133], v38 offset:2048
	ds_read_b128 v[134:137], v38 offset:3072
	s_add_u32 s12, s12, 0x40000
	s_addc_u32 s13, s13, 0
	s_mov_b32 m0, s76
	ds_read_b128 v[170:173], v242 offset:32768
	ds_read_b128 v[174:177], v242 offset:33792
	ds_read_b128 v[178:181], v242 offset:34816
	ds_read_b128 v[194:197], v242 offset:35840
	ds_read_b128 v[198:201], v242 offset:36864
	ds_read_b128 v[208:211], v242 offset:37888
	ds_read_b128 v[218:221], v242 offset:38912
	ds_read_b128 v[244:247], v242 offset:39936
	global_load_lds_dwordx4 v36, s[12:13]
	s_mov_b32 m0, s77
	s_nop 0
	global_load_lds_dwordx4 v186, s[12:13]
	s_waitcnt vmcnt(8)
	s_waitcnt lgkmcnt(0)
	s_barrier
	s_setprio 1
	s_waitcnt lgkmcnt(0)
	v_mfma_f32_16x16x32_bf16 v[166:169], v[106:109], v[170:173], v[166:169]
	v_mfma_f32_16x16x32_bf16 v[70:73], v[114:117], v[170:173], v[70:73]
	v_mfma_f32_16x16x32_bf16 v[158:161], v[106:109], v[178:181], v[158:161]
	v_mfma_f32_16x16x32_bf16 v[62:65], v[114:117], v[178:181], v[62:65]
	v_mfma_f32_16x16x32_bf16 v[150:153], v[106:109], v[198:201], v[150:153]
	v_mfma_f32_16x16x32_bf16 v[54:57], v[114:117], v[198:201], v[54:57]
	v_mfma_f32_16x16x32_bf16 v[142:145], v[106:109], v[218:221], v[142:145]
	v_mfma_f32_16x16x32_bf16 v[46:49], v[114:117], v[218:221], v[46:49]
	v_mfma_f32_16x16x32_bf16 v[166:169], v[110:113], v[174:177], v[166:169]
	v_mfma_f32_16x16x32_bf16 v[70:73], v[118:121], v[174:177], v[70:73]
	v_mfma_f32_16x16x32_bf16 v[158:161], v[110:113], v[194:197], v[158:161]
	v_mfma_f32_16x16x32_bf16 v[62:65], v[118:121], v[194:197], v[62:65]
	v_mfma_f32_16x16x32_bf16 v[150:153], v[110:113], v[208:211], v[150:153]
	v_mfma_f32_16x16x32_bf16 v[54:57], v[118:121], v[208:211], v[54:57]
	v_mfma_f32_16x16x32_bf16 v[142:145], v[110:113], v[244:247], v[142:145]
	v_mfma_f32_16x16x32_bf16 v[46:49], v[118:121], v[244:247], v[46:49]
	s_setprio 0
	s_setprio 1
	v_mfma_f32_16x16x32_bf16 v[162:165], v[122:125], v[170:173], v[162:165]
	v_mfma_f32_16x16x32_bf16 v[66:69], v[130:133], v[170:173], v[66:69]
	v_mfma_f32_16x16x32_bf16 v[154:157], v[122:125], v[178:181], v[154:157]
	v_mfma_f32_16x16x32_bf16 v[58:61], v[130:133], v[178:181], v[58:61]
	v_mfma_f32_16x16x32_bf16 v[146:149], v[122:125], v[198:201], v[146:149]
	v_mfma_f32_16x16x32_bf16 v[50:53], v[130:133], v[198:201], v[50:53]
	v_mfma_f32_16x16x32_bf16 v[138:141], v[122:125], v[218:221], v[138:141]
	v_mfma_f32_16x16x32_bf16 v[42:45], v[130:133], v[218:221], v[42:45]
	v_mfma_f32_16x16x32_bf16 v[162:165], v[126:129], v[174:177], v[162:165]
	v_mfma_f32_16x16x32_bf16 v[66:69], v[134:137], v[174:177], v[66:69]
	v_mfma_f32_16x16x32_bf16 v[154:157], v[126:129], v[194:197], v[154:157]
	v_mfma_f32_16x16x32_bf16 v[58:61], v[134:137], v[194:197], v[58:61]
	v_mfma_f32_16x16x32_bf16 v[146:149], v[126:129], v[208:211], v[146:149]
	v_mfma_f32_16x16x32_bf16 v[50:53], v[134:137], v[208:211], v[50:53]
	v_mfma_f32_16x16x32_bf16 v[138:141], v[126:129], v[244:247], v[138:141]
	v_mfma_f32_16x16x32_bf16 v[42:45], v[134:137], v[244:247], v[42:45]
	s_setprio 0
	s_barrier
; #define PG8_STAGE(bufoff, gbase, voff) do { _Pragma("unroll") for (int _i = 0; _i < 2; ++_i) \
;         __builtin_amdgcn_global_load_lds((const unsigned*)((const char*)(gbase) + (voff)[_i]), (PG8_LAS unsigned*)(lds + (bufoff) + ldsw + _i * 8192), 16, 0, 0); } while (0)
; #define PG8_LDA(dst, b, h) do { _Pragma("unroll") for (int m = 0; m < 4; ++m) _Pragma("unroll") for (int k = 0; k < 2; ++k) dst[m][k] = *(const PG8_LAS bf16x8*)(lds + PG8_SA(b, h) + aoff + m * 2048 + k * 1024); } while (0)
; #define PG8_LDB(dst, b, h) do { _Pragma("unroll") for (int n = 0; n < 2; ++n) _Pragma("unroll") for (int k = 0; k < 2; ++k) dst[n][k] = *(const PG8_LAS bf16x8*)(lds + PG8_SB(b, h) + boff + n * 2048 + k * 1024); } while (0)
; #define PG8_MMA(ai, bj, At, Bt) do { __builtin_amdgcn_s_setprio(1); _Pragma("unroll") for (int m = 0; m < 4; ++m) _Pragma("unroll") for (int n = 0; n < 2; ++n) _Pragma("unroll") for (int k = 0; k < 2; ++k) \
;         acc[ai][bj][m][n] = __builtin_amdgcn_mfma_f32_16x16x32_bf16(Bt[n][k], At[m][k], acc[ai][bj][m][n], 0, 0, 0); __builtin_amdgcn_s_setprio(0); } while (0)
; #define PG8_WAIT_V(n) asm volatile("s_waitcnt vmcnt(" #n ")" ::: "memory")
; template <class Epi, class Sched, bool ALIGN_EPI = false, bool SP2 = false>
; __device__ __forceinline__ void gemm_phase(PG8_LAS unsigned char* lds, const Gemm g, const Sched& S, const Epi& E) {
;     ...
;             PG8_LDB(B0, 0, 0); PG8_LDB(B1, 0, 1); PG8_SCHED; PG8_LDA(At, 0, 0); PG8_STAGE(PG8_SA(1, 1), a1 + hstep, voffA);
;             PG8_WAIT_V(8); PG8_WAIT_L(0); PG8_BAR; PG8_MMA(0, 0, At, B0); PG8_MMA(0, 1, At, B1); PG8_BAR; PG8_SCHED;
;             PG8_LDA(At, 0, 1); PG8_STAGE(PG8_SB(0, 0), b2, voffB); PG8_STAGE(PG8_SB(0, 1), b2 + hstep, voffB); PG8_STAGE(PG8_SA(0, 0), a2, voffA);
;             PG8_WAIT_V(8); PG8_WAIT_L(0); PG8_BAR; PG8_MMA(1, 0, At, B0); PG8_MMA(1, 1, At, B1); PG8_BAR; PG8_SCHED;
;             PG8_LDB(B0, 1, 0); PG8_LDB(B1, 1, 1); PG8_SCHED; PG8_LDA(At, 1, 0); PG8_STAGE(PG8_SA(0, 1), a2 + hstep, voffA);
;             PG8_WAIT_V(8); PG8_WAIT_L(0); PG8_BAR; PG8_MMA(0, 0, At, B0); PG8_MMA(0, 1, At, B1); PG8_BAR; PG8_SCHED;
;             PG8_LDA(At, 1, 1); PG8_STAGE(PG8_SB(1, 0), b3, voffB); PG8_STAGE(PG8_SB(1, 1), b3 + hstep, voffB); PG8_STAGE(PG8_SA(1, 0), a3, voffA);
;             PG8_WAIT_V(8); PG8_WAIT_L(0); PG8_BAR; PG8_MMA(1, 0, At, B0); PG8_MMA(1, 1, At, B1); PG8_BAR; PG8_SCHED;
	s_add_i32 s12, s19, s59
	v_lshl_add_u64 v[38:39], v[202:203], 0, s[70:71]
	s_mov_b32 m0, s12
	ds_read_b128 v[170:173], v242 offset:49152
	ds_read_b128 v[174:177], v242 offset:50176
	ds_read_b128 v[178:181], v242 offset:51200
	ds_read_b128 v[194:197], v242 offset:52224
	ds_read_b128 v[198:201], v242 offset:53248
	ds_read_b128 v[208:211], v242 offset:54272
	ds_read_b128 v[218:221], v242 offset:55296
	ds_read_b128 v[244:247], v242 offset:56320
	global_load_lds_dwordx4 v[38:39], off
	s_add_i32 m0, s12, 0x2000
	s_add_u32 s10, s10, 0x40080
	v_lshl_add_u64 v[38:39], v[212:213], 0, s[70:71]
	s_addc_u32 s11, s11, 0
	s_add_i32 s12, s20, s59
	global_load_lds_dwordx4 v[38:39], off
	s_mov_b32 m0, s12
	s_nop 0
	global_load_lds_dwordx4 v34, s[10:11]
	s_add_i32 m0, s12, 0x2000
	s_nop 0
	global_load_lds_dwordx4 v188, s[10:11]
	v_lshl_add_u64 v[38:39], v[248:249], 0, s[70:71]
	s_mov_b32 m0, s82
	s_nop 0
	global_load_lds_dwordx4 v[38:39], off
	v_lshl_add_u64 v[38:39], v[250:251], 0, s[70:71]
	s_mov_b32 m0, s83
	s_nop 0
	global_load_lds_dwordx4 v[38:39], off
	s_waitcnt vmcnt(8)
	s_waitcnt lgkmcnt(0)
	s_barrier
	s_setprio 1
	s_waitcnt lgkmcnt(0)
	v_mfma_f32_16x16x32_bf16 v[102:105], v[106:109], v[170:173], v[102:105]
	v_mfma_f32_16x16x32_bf16 v[30:33], v[114:117], v[170:173], v[30:33]
	v_mfma_f32_16x16x32_bf16 v[94:97], v[106:109], v[178:181], v[94:97]
	v_mfma_f32_16x16x32_bf16 v[22:25], v[114:117], v[178:181], v[22:25]
	v_mfma_f32_16x16x32_bf16 v[86:89], v[106:109], v[198:201], v[86:89]
	v_mfma_f32_16x16x32_bf16 v[14:17], v[114:117], v[198:201], v[14:17]
	v_mfma_f32_16x16x32_bf16 v[78:81], v[106:109], v[218:221], v[78:81]
	v_mfma_f32_16x16x32_bf16 v[6:9], v[114:117], v[218:221], v[6:9]
	v_mfma_f32_16x16x32_bf16 v[102:105], v[110:113], v[174:177], v[102:105]
	v_mfma_f32_16x16x32_bf16 v[30:33], v[118:121], v[174:177], v[30:33]
	v_mfma_f32_16x16x32_bf16 v[94:97], v[110:113], v[194:197], v[94:97]
	v_mfma_f32_16x16x32_bf16 v[22:25], v[118:121], v[194:197], v[22:25]
	v_mfma_f32_16x16x32_bf16 v[86:89], v[110:113], v[208:211], v[86:89]
	v_mfma_f32_16x16x32_bf16 v[14:17], v[118:121], v[208:211], v[14:17]
	v_mfma_f32_16x16x32_bf16 v[78:81], v[110:113], v[244:247], v[78:81]
	v_mfma_f32_16x16x32_bf16 v[6:9], v[118:121], v[244:247], v[6:9]
	s_setprio 0
	s_setprio 1
	v_mfma_f32_16x16x32_bf16 v[98:101], v[122:125], v[170:173], v[98:101]
	v_mfma_f32_16x16x32_bf16 v[26:29], v[130:133], v[170:173], v[26:29]
	v_mfma_f32_16x16x32_bf16 v[90:93], v[122:125], v[178:181], v[90:93]
	v_mfma_f32_16x16x32_bf16 v[18:21], v[130:133], v[178:181], v[18:21]
	v_mfma_f32_16x16x32_bf16 v[82:85], v[122:125], v[198:201], v[82:85]
	v_mfma_f32_16x16x32_bf16 v[10:13], v[130:133], v[198:201], v[10:13]
	v_mfma_f32_16x16x32_bf16 v[74:77], v[122:125], v[218:221], v[74:77]
	v_mfma_f32_16x16x32_bf16 v[2:5], v[130:133], v[218:221], v[2:5]
	v_mfma_f32_16x16x32_bf16 v[98:101], v[126:129], v[174:177], v[98:101]
	v_mfma_f32_16x16x32_bf16 v[26:29], v[134:137], v[174:177], v[26:29]
	v_mfma_f32_16x16x32_bf16 v[90:93], v[126:129], v[194:197], v[90:93]
	v_mfma_f32_16x16x32_bf16 v[18:21], v[134:137], v[194:197], v[18:21]
	v_mfma_f32_16x16x32_bf16 v[82:85], v[126:129], v[208:211], v[82:85]
	v_mfma_f32_16x16x32_bf16 v[10:13], v[134:137], v[208:211], v[10:13]
	v_mfma_f32_16x16x32_bf16 v[74:77], v[126:129], v[244:247], v[74:77]
	v_mfma_f32_16x16x32_bf16 v[2:5], v[134:137], v[244:247], v[2:5]
	s_setprio 0
	s_barrier
	s_add_i32 s17, s17, 2
	s_add_u32 s0, s0, 0x100
	s_addc_u32 s1, s1, 0
	s_add_u32 s15, s15, 0x100
	s_addc_u32 s16, s16, 0
	s_cmp_gt_u32 s17, 13
.LBB0_697:
	s_add_u32 s10, s0, 0xfffc0080
	s_addc_u32 s11, s1, -1
	s_add_i32 s19, 0, 0x10000
	s_cmp_eq_u32 s17, 12
	s_cselect_b32 s13, s95, s11
	s_cselect_b32 s12, s94, s10
	v_add_u32_e32 v38, s19, v228
	s_cselect_b32 s11, s3, s16
	s_cselect_b32 s10, s14, s15
	s_add_i32 s22, 0, 0x14000
	ds_read_b128 v[106:109], v38
	ds_read_b128 v[110:113], v38 offset:1024
	ds_read_b128 v[114:117], v38 offset:2048
	ds_read_b128 v[118:121], v38 offset:3072
	v_add_u32_e32 v38, s22, v228
	ds_read_b128 v[122:125], v38
	ds_read_b128 v[126:129], v38 offset:1024
	ds_read_b128 v[130:133], v38 offset:2048
	ds_read_b128 v[134:137], v38 offset:3072
	s_add_i32 m0, s80, 0xc000
	ds_read_b128 v[170:173], v242
	ds_read_b128 v[174:177], v242 offset:1024
	ds_read_b128 v[178:181], v242 offset:2048
	ds_read_b128 v[194:197], v242 offset:3072
	ds_read_b128 v[198:201], v242 offset:4096
	ds_read_b128 v[208:211], v242 offset:5120
	ds_read_b128 v[218:221], v242 offset:6144
	ds_read_b128 v[244:247], v242 offset:7168
	global_load_lds_dwordx4 v190, s[0:1]
	s_add_i32 m0, s80, 0xe000
	s_nop 0
	global_load_lds_dwordx4 v192, s[0:1]
	s_waitcnt vmcnt(8)
	s_waitcnt lgkmcnt(0)
	s_barrier
; #define PG8_STAGE(bufoff, gbase, voff) do { _Pragma("unroll") for (int _i = 0; _i < 2; ++_i) \
;         __builtin_amdgcn_global_load_lds((const unsigned*)((const char*)(gbase) + (voff)[_i]), (PG8_LAS unsigned*)(lds + (bufoff) + ldsw + _i * 8192), 16, 0, 0); } while (0)
; #define PG8_LDA(dst, b, h) do { _Pragma("unroll") for (int m = 0; m < 4; ++m) _Pragma("unroll") for (int k = 0; k < 2; ++k) dst[m][k] = *(const PG8_LAS bf16x8*)(lds + PG8_SA(b, h) + aoff + m * 2048 + k * 1024); } while (0)
; #define PG8_MMA(ai, bj, At, Bt) do { __builtin_amdgcn_s_setprio(1); _Pragma("unroll") for (int m = 0; m < 4; ++m) _Pragma("unroll") for (int n = 0; n < 2; ++n) _Pragma("unroll") for (int k = 0; k < 2; ++k) \
;         acc[ai][bj][m][n] = __builtin_amdgcn_mfma_f32_16x16x32_bf16(Bt[n][k], At[m][k], acc[ai][bj][m][n], 0, 0, 0); __builtin_amdgcn_s_setprio(0); } while (0)
; #define PG8_WAIT_V(n) asm volatile("s_waitcnt vmcnt(" #n ")" ::: "memory")
; #define PG8_WAIT_L(n) asm volatile("s_waitcnt lgkmcnt(" #n ")" ::: "memory")
; #define PG8_BAR __builtin_amdgcn_s_barrier()
; #define PG8_SCHED __builtin_amdgcn_sched_barrier(0)
; template <class Epi, class Sched, bool ALIGN_EPI = false, bool SP2 = false>
; __device__ __forceinline__ void gemm_phase(PG8_LAS unsigned char* lds, const Gemm g, const Sched& S, const Epi& E) {
;     ...
;             PG8_WAIT_V(8); PG8_WAIT_L(0); PG8_BAR; PG8_MMA(0, 0, At, B0); PG8_MMA(0, 1, At, B1); PG8_BAR; PG8_SCHED;
;             PG8_LDA(At, 0, 1); PG8_STAGE(PG8_SB(0, 0), b2, voffB); PG8_STAGE(PG8_SB(0, 1), b2 + hstep, voffB); PG8_STAGE(PG8_SA(0, 0), a2, voffA);
;             PG8_WAIT_V(8); PG8_WAIT_L(0); PG8_BAR; PG8_MMA(1, 0, At, B0); PG8_MMA(1, 1, At, B1); PG8_BAR; PG8_SCHED;
	s_setprio 1
	s_waitcnt lgkmcnt(0)
	v_mfma_f32_16x16x32_bf16 v[166:169], v[106:109], v[170:173], v[166:169]
	v_mfma_f32_16x16x32_bf16 v[70:73], v[114:117], v[170:173], v[70:73]
	v_mfma_f32_16x16x32_bf16 v[158:161], v[106:109], v[178:181], v[158:161]
	v_mfma_f32_16x16x32_bf16 v[62:65], v[114:117], v[178:181], v[62:65]
	v_mfma_f32_16x16x32_bf16 v[150:153], v[106:109], v[198:201], v[150:153]
	v_mfma_f32_16x16x32_bf16 v[54:57], v[114:117], v[198:201], v[54:57]
	v_mfma_f32_16x16x32_bf16 v[142:145], v[106:109], v[218:221], v[142:145]
	v_mfma_f32_16x16x32_bf16 v[46:49], v[114:117], v[218:221], v[46:49]
	v_mfma_f32_16x16x32_bf16 v[166:169], v[110:113], v[174:177], v[166:169]
	v_mfma_f32_16x16x32_bf16 v[70:73], v[118:121], v[174:177], v[70:73]
	v_mfma_f32_16x16x32_bf16 v[158:161], v[110:113], v[194:197], v[158:161]
	v_mfma_f32_16x16x32_bf16 v[62:65], v[118:121], v[194:197], v[62:65]
	v_mfma_f32_16x16x32_bf16 v[150:153], v[110:113], v[208:211], v[150:153]
	v_mfma_f32_16x16x32_bf16 v[54:57], v[118:121], v[208:211], v[54:57]
	v_mfma_f32_16x16x32_bf16 v[142:145], v[110:113], v[244:247], v[142:145]
	v_mfma_f32_16x16x32_bf16 v[46:49], v[118:121], v[244:247], v[46:49]
	s_setprio 0
	s_setprio 1
	v_mfma_f32_16x16x32_bf16 v[162:165], v[122:125], v[170:173], v[162:165]
	v_mfma_f32_16x16x32_bf16 v[66:69], v[130:133], v[170:173], v[66:69]
	v_mfma_f32_16x16x32_bf16 v[154:157], v[122:125], v[178:181], v[154:157]
	v_mfma_f32_16x16x32_bf16 v[58:61], v[130:133], v[178:181], v[58:61]
	v_mfma_f32_16x16x32_bf16 v[146:149], v[122:125], v[198:201], v[146:149]
	v_mfma_f32_16x16x32_bf16 v[50:53], v[130:133], v[198:201], v[50:53]
	v_mfma_f32_16x16x32_bf16 v[138:141], v[122:125], v[218:221], v[138:141]
	v_mfma_f32_16x16x32_bf16 v[42:45], v[130:133], v[218:221], v[42:45]
	v_mfma_f32_16x16x32_bf16 v[162:165], v[126:129], v[174:177], v[162:165]
	v_mfma_f32_16x16x32_bf16 v[66:69], v[134:137], v[174:177], v[66:69]
	v_mfma_f32_16x16x32_bf16 v[154:157], v[126:129], v[194:197], v[154:157]
	v_mfma_f32_16x16x32_bf16 v[58:61], v[134:137], v[194:197], v[58:61]
	v_mfma_f32_16x16x32_bf16 v[146:149], v[126:129], v[208:211], v[146:149]
	v_mfma_f32_16x16x32_bf16 v[50:53], v[134:137], v[208:211], v[50:53]
	v_mfma_f32_16x16x32_bf16 v[138:141], v[126:129], v[244:247], v[138:141]
	v_mfma_f32_16x16x32_bf16 v[42:45], v[134:137], v[244:247], v[42:45]
	s_setprio 0
	s_barrier
	s_add_i32 s19, s19, s59
	v_lshl_add_u64 v[202:203], s[10:11], 0, v[34:35]
	s_mov_b32 m0, s19
	ds_read_b128 v[170:173], v242 offset:16384
	ds_read_b128 v[174:177], v242 offset:17408
	ds_read_b128 v[178:181], v242 offset:18432
	ds_read_b128 v[194:197], v242 offset:19456
	ds_read_b128 v[198:201], v242 offset:20480
	ds_read_b128 v[208:211], v242 offset:21504
	ds_read_b128 v[218:221], v242 offset:22528
	ds_read_b128 v[244:247], v242 offset:23552
	global_load_lds_dwordx4 v[202:203], off
	s_add_i32 m0, s19, 0x2000
	s_add_u32 s20, s10, 0x40000
	v_lshl_add_u64 v[212:213], s[10:11], 0, v[188:189]
	s_addc_u32 s21, s11, 0
	s_add_i32 s19, s22, s59
	global_load_lds_dwordx4 v[212:213], off
	s_mov_b32 m0, s19
	v_lshl_add_u64 v[250:251], s[12:13], 0, v[186:187]
	global_load_lds_dwordx4 v34, s[20:21]
	s_add_i32 m0, s19, 0x2000
	s_nop 0
	global_load_lds_dwordx4 v188, s[20:21]
	v_lshl_add_u64 v[248:249], s[12:13], 0, v[36:37]
	s_mov_b32 m0, s80
	s_nop 0
	global_load_lds_dwordx4 v[248:249], off
	s_mov_b32 m0, s81
	s_nop 0
	global_load_lds_dwordx4 v[250:251], off
	s_waitcnt vmcnt(8)
	s_waitcnt lgkmcnt(0)
	s_barrier
	s_setprio 1
	s_waitcnt lgkmcnt(0)
	v_mfma_f32_16x16x32_bf16 v[102:105], v[106:109], v[170:173], v[102:105]
	v_mfma_f32_16x16x32_bf16 v[30:33], v[114:117], v[170:173], v[30:33]
	v_mfma_f32_16x16x32_bf16 v[94:97], v[106:109], v[178:181], v[94:97]
	v_mfma_f32_16x16x32_bf16 v[22:25], v[114:117], v[178:181], v[22:25]
	v_mfma_f32_16x16x32_bf16 v[86:89], v[106:109], v[198:201], v[86:89]
	v_mfma_f32_16x16x32_bf16 v[14:17], v[114:117], v[198:201], v[14:17]
	v_mfma_f32_16x16x32_bf16 v[78:81], v[106:109], v[218:221], v[78:81]
	v_mfma_f32_16x16x32_bf16 v[6:9], v[114:117], v[218:221], v[6:9]
	v_mfma_f32_16x16x32_bf16 v[102:105], v[110:113], v[174:177], v[102:105]
	v_mfma_f32_16x16x32_bf16 v[30:33], v[118:121], v[174:177], v[30:33]
	v_mfma_f32_16x16x32_bf16 v[94:97], v[110:113], v[194:197], v[94:97]
	v_mfma_f32_16x16x32_bf16 v[22:25], v[118:121], v[194:197], v[22:25]
	v_mfma_f32_16x16x32_bf16 v[86:89], v[110:113], v[208:211], v[86:89]
	v_mfma_f32_16x16x32_bf16 v[14:17], v[118:121], v[208:211], v[14:17]
	v_mfma_f32_16x16x32_bf16 v[78:81], v[110:113], v[244:247], v[78:81]
	v_mfma_f32_16x16x32_bf16 v[6:9], v[118:121], v[244:247], v[6:9]
	s_setprio 0
	s_setprio 1
	v_mfma_f32_16x16x32_bf16 v[98:101], v[122:125], v[170:173], v[98:101]
	v_mfma_f32_16x16x32_bf16 v[26:29], v[130:133], v[170:173], v[26:29]
	v_mfma_f32_16x16x32_bf16 v[90:93], v[122:125], v[178:181], v[90:93]
	v_mfma_f32_16x16x32_bf16 v[18:21], v[130:133], v[178:181], v[18:21]
	v_mfma_f32_16x16x32_bf16 v[82:85], v[122:125], v[198:201], v[82:85]
	v_mfma_f32_16x16x32_bf16 v[10:13], v[130:133], v[198:201], v[10:13]
	v_mfma_f32_16x16x32_bf16 v[74:77], v[122:125], v[218:221], v[74:77]
	v_mfma_f32_16x16x32_bf16 v[2:5], v[130:133], v[218:221], v[2:5]
	v_mfma_f32_16x16x32_bf16 v[98:101], v[126:129], v[174:177], v[98:101]
	v_mfma_f32_16x16x32_bf16 v[26:29], v[134:137], v[174:177], v[26:29]
	v_mfma_f32_16x16x32_bf16 v[90:93], v[126:129], v[194:197], v[90:93]
	v_mfma_f32_16x16x32_bf16 v[18:21], v[134:137], v[194:197], v[18:21]
	v_mfma_f32_16x16x32_bf16 v[82:85], v[126:129], v[208:211], v[82:85]
	v_mfma_f32_16x16x32_bf16 v[10:13], v[134:137], v[208:211], v[10:13]
	v_mfma_f32_16x16x32_bf16 v[74:77], v[126:129], v[244:247], v[74:77]
	v_mfma_f32_16x16x32_bf16 v[2:5], v[134:137], v[244:247], v[2:5]
	s_setprio 0
	s_barrier
; #define PG8_STAGE(bufoff, gbase, voff) do { _Pragma("unroll") for (int _i = 0; _i < 2; ++_i) \
;         __builtin_amdgcn_global_load_lds((const unsigned*)((const char*)(gbase) + (voff)[_i]), (PG8_LAS unsigned*)(lds + (bufoff) + ldsw + _i * 8192), 16, 0, 0); } while (0)
; #define PG8_LDA(dst, b, h) do { _Pragma("unroll") for (int m = 0; m < 4; ++m) _Pragma("unroll") for (int k = 0; k < 2; ++k) dst[m][k] = *(const PG8_LAS bf16x8*)(lds + PG8_SA(b, h) + aoff + m * 2048 + k * 1024); } while (0)
; #define PG8_LDB(dst, b, h) do { _Pragma("unroll") for (int n = 0; n < 2; ++n) _Pragma("unroll") for (int k = 0; k < 2; ++k) dst[n][k] = *(const PG8_LAS bf16x8*)(lds + PG8_SB(b, h) + boff + n * 2048 + k * 1024); } while (0)
; #define PG8_MMA(ai, bj, At, Bt) do { __builtin_amdgcn_s_setprio(1); _Pragma("unroll") for (int m = 0; m < 4; ++m) _Pragma("unroll") for (int n = 0; n < 2; ++n) _Pragma("unroll") for (int k = 0; k < 2; ++k) \
;         acc[ai][bj][m][n] = __builtin_amdgcn_mfma_f32_16x16x32_bf16(Bt[n][k], At[m][k], acc[ai][bj][m][n], 0, 0, 0); __builtin_amdgcn_s_setprio(0); } while (0)
; #define PG8_WAIT_V(n) asm volatile("s_waitcnt vmcnt(" #n ")" ::: "memory")
; #define PG8_WAIT_L(n) asm volatile("s_waitcnt lgkmcnt(" #n ")" ::: "memory")
; #define PG8_BAR __builtin_amdgcn_s_barrier()
; #define PG8_SCHED __builtin_amdgcn_sched_barrier(0)
; template <class Epi, class Sched, bool ALIGN_EPI = false, bool SP2 = false>
; __device__ __forceinline__ void gemm_phase(PG8_LAS unsigned char* lds, const Gemm g, const Sched& S, const Epi& E) {
;     ...
;             PG8_WAIT_V(8); PG8_WAIT_L(0); PG8_BAR; PG8_MMA(1, 0, At, B0); PG8_MMA(1, 1, At, B1); PG8_BAR; PG8_SCHED;
;             PG8_LDB(B0, 1, 0); PG8_LDB(B1, 1, 1); PG8_SCHED; PG8_LDA(At, 1, 0); PG8_STAGE(PG8_SA(0, 1), a2 + hstep, voffA);
;             PG8_WAIT_V(8); PG8_WAIT_L(0); PG8_BAR; PG8_MMA(0, 0, At, B0); PG8_MMA(0, 1, At, B1); PG8_BAR; PG8_SCHED;
	s_add_i32 s19, 0, 0x18000
	v_add_u32_e32 v38, s19, v228
	s_add_i32 s20, 0, 0x1c000
	ds_read_b128 v[106:109], v38
	ds_read_b128 v[110:113], v38 offset:1024
	ds_read_b128 v[114:117], v38 offset:2048
	ds_read_b128 v[118:121], v38 offset:3072
	v_add_u32_e32 v38, s20, v228
	ds_read_b128 v[122:125], v38
	ds_read_b128 v[126:129], v38 offset:1024
	ds_read_b128 v[130:133], v38 offset:2048
	ds_read_b128 v[134:137], v38 offset:3072
	s_add_u32 s12, s12, 0x40000
	s_addc_u32 s13, s13, 0
	s_mov_b32 m0, s76
	ds_read_b128 v[170:173], v242 offset:32768
	ds_read_b128 v[174:177], v242 offset:33792
	ds_read_b128 v[178:181], v242 offset:34816
	ds_read_b128 v[194:197], v242 offset:35840
	ds_read_b128 v[198:201], v242 offset:36864
	ds_read_b128 v[208:211], v242 offset:37888
	ds_read_b128 v[218:221], v242 offset:38912
	ds_read_b128 v[244:247], v242 offset:39936
	global_load_lds_dwordx4 v36, s[12:13]
	s_mov_b32 m0, s77
	s_nop 0
	global_load_lds_dwordx4 v186, s[12:13]
	s_waitcnt vmcnt(8)
	s_waitcnt lgkmcnt(0)
	s_barrier
	s_setprio 1
	s_waitcnt lgkmcnt(0)
	v_mfma_f32_16x16x32_bf16 v[166:169], v[106:109], v[170:173], v[166:169]
	v_mfma_f32_16x16x32_bf16 v[70:73], v[114:117], v[170:173], v[70:73]
	v_mfma_f32_16x16x32_bf16 v[158:161], v[106:109], v[178:181], v[158:161]
	v_mfma_f32_16x16x32_bf16 v[62:65], v[114:117], v[178:181], v[62:65]
	v_mfma_f32_16x16x32_bf16 v[150:153], v[106:109], v[198:201], v[150:153]
	v_mfma_f32_16x16x32_bf16 v[54:57], v[114:117], v[198:201], v[54:57]
	v_mfma_f32_16x16x32_bf16 v[142:145], v[106:109], v[218:221], v[142:145]
	v_mfma_f32_16x16x32_bf16 v[46:49], v[114:117], v[218:221], v[46:49]
	v_mfma_f32_16x16x32_bf16 v[166:169], v[110:113], v[174:177], v[166:169]
	v_mfma_f32_16x16x32_bf16 v[70:73], v[118:121], v[174:177], v[70:73]
	v_mfma_f32_16x16x32_bf16 v[158:161], v[110:113], v[194:197], v[158:161]
	v_mfma_f32_16x16x32_bf16 v[62:65], v[118:121], v[194:197], v[62:65]
	v_mfma_f32_16x16x32_bf16 v[150:153], v[110:113], v[208:211], v[150:153]
	v_mfma_f32_16x16x32_bf16 v[54:57], v[118:121], v[208:211], v[54:57]
	v_mfma_f32_16x16x32_bf16 v[142:145], v[110:113], v[244:247], v[142:145]
	v_mfma_f32_16x16x32_bf16 v[46:49], v[118:121], v[244:247], v[46:49]
	s_setprio 0
	s_setprio 1
	v_mfma_f32_16x16x32_bf16 v[162:165], v[122:125], v[170:173], v[162:165]
	v_mfma_f32_16x16x32_bf16 v[66:69], v[130:133], v[170:173], v[66:69]
	v_mfma_f32_16x16x32_bf16 v[154:157], v[122:125], v[178:181], v[154:157]
	v_mfma_f32_16x16x32_bf16 v[58:61], v[130:133], v[178:181], v[58:61]
	v_mfma_f32_16x16x32_bf16 v[146:149], v[122:125], v[198:201], v[146:149]
	v_mfma_f32_16x16x32_bf16 v[50:53], v[130:133], v[198:201], v[50:53]
	v_mfma_f32_16x16x32_bf16 v[138:141], v[122:125], v[218:221], v[138:141]
	v_mfma_f32_16x16x32_bf16 v[42:45], v[130:133], v[218:221], v[42:45]
	v_mfma_f32_16x16x32_bf16 v[162:165], v[126:129], v[174:177], v[162:165]
	v_mfma_f32_16x16x32_bf16 v[66:69], v[134:137], v[174:177], v[66:69]
	v_mfma_f32_16x16x32_bf16 v[154:157], v[126:129], v[194:197], v[154:157]
	v_mfma_f32_16x16x32_bf16 v[58:61], v[134:137], v[194:197], v[58:61]
	v_mfma_f32_16x16x32_bf16 v[146:149], v[126:129], v[208:211], v[146:149]
	v_mfma_f32_16x16x32_bf16 v[50:53], v[134:137], v[208:211], v[50:53]
	v_mfma_f32_16x16x32_bf16 v[138:141], v[126:129], v[244:247], v[138:141]
	v_mfma_f32_16x16x32_bf16 v[42:45], v[134:137], v[244:247], v[42:45]
	s_setprio 0
	s_barrier
; #define PG8_STAGE(bufoff, gbase, voff) do { _Pragma("unroll") for (int _i = 0; _i < 2; ++_i) \
;         __builtin_amdgcn_global_load_lds((const unsigned*)((const char*)(gbase) + (voff)[_i]), (PG8_LAS unsigned*)(lds + (bufoff) + ldsw + _i * 8192), 16, 0, 0); } while (0)
; #define PG8_LDA(dst, b, h) do { _Pragma("unroll") for (int m = 0; m < 4; ++m) _Pragma("unroll") for (int k = 0; k < 2; ++k) dst[m][k] = *(const PG8_LAS bf16x8*)(lds + PG8_SA(b, h) + aoff + m * 2048 + k * 1024); } while (0)
; #define PG8_MMA(ai, bj, At, Bt) do { __builtin_amdgcn_s_setprio(1); _Pragma("unroll") for (int m = 0; m < 4; ++m) _Pragma("unroll") for (int n = 0; n < 2; ++n) _Pragma("unroll") for (int k = 0; k < 2; ++k) \
;         acc[ai][bj][m][n] = __builtin_amdgcn_mfma_f32_16x16x32_bf16(Bt[n][k], At[m][k], acc[ai][bj][m][n], 0, 0, 0); __builtin_amdgcn_s_setprio(0); } while (0)
; #define PG8_WAIT_V(n) asm volatile("s_waitcnt vmcnt(" #n ")" ::: "memory")
; #define PG8_WAIT_L(n) asm volatile("s_waitcnt lgkmcnt(" #n ")" ::: "memory")
; #define PG8_BAR __builtin_amdgcn_s_barrier()
; #define PG8_SCHED __builtin_amdgcn_sched_barrier(0)
; template <class Epi, class Sched, bool ALIGN_EPI = false, bool SP2 = false>
; __device__ __forceinline__ void gemm_phase(PG8_LAS unsigned char* lds, const Gemm g, const Sched& S, const Epi& E) {
;     ...
;             PG8_WAIT_V(8); PG8_WAIT_L(0); PG8_BAR; PG8_MMA(0, 0, At, B0); PG8_MMA(0, 1, At, B1); PG8_BAR; PG8_SCHED;
;             PG8_LDA(At, 1, 1); PG8_STAGE(PG8_SB(1, 0), b3, voffB); PG8_STAGE(PG8_SB(1, 1), b3 + hstep, voffB); PG8_STAGE(PG8_SA(1, 0), a3, voffA);
;             PG8_WAIT_V(8); PG8_WAIT_L(0); PG8_BAR; PG8_MMA(1, 0, At, B0); PG8_MMA(1, 1, At, B1); PG8_BAR; PG8_SCHED;
;     ...
;         if constexpr (ALIGN_EPI) { if (wr == 0) PG8_BAR; }
;         if constexpr (!Epi::AFTER_DRAIN) { E(acc, cur, wr, wc, fr, fq); S.done(cur); }
	s_add_i32 s12, s19, s59
	v_lshl_add_u64 v[38:39], v[202:203], 0, s[70:71]
	s_mov_b32 m0, s12
	ds_read_b128 v[170:173], v242 offset:49152
	ds_read_b128 v[174:177], v242 offset:50176
	ds_read_b128 v[178:181], v242 offset:51200
	ds_read_b128 v[194:197], v242 offset:52224
	ds_read_b128 v[198:201], v242 offset:53248
	ds_read_b128 v[208:211], v242 offset:54272
	ds_read_b128 v[218:221], v242 offset:55296
	ds_read_b128 v[244:247], v242 offset:56320
	global_load_lds_dwordx4 v[38:39], off
	s_add_i32 m0, s12, 0x2000
	s_add_u32 s10, s10, 0x40080
	v_lshl_add_u64 v[38:39], v[212:213], 0, s[70:71]
	s_addc_u32 s11, s11, 0
	s_add_i32 s12, s20, s59
	global_load_lds_dwordx4 v[38:39], off
	s_mov_b32 m0, s12
	s_nop 0
	global_load_lds_dwordx4 v34, s[10:11]
	s_add_i32 m0, s12, 0x2000
	s_nop 0
	global_load_lds_dwordx4 v188, s[10:11]
	v_lshl_add_u64 v[38:39], v[248:249], 0, s[70:71]
	s_mov_b32 m0, s82
	s_nop 0
	global_load_lds_dwordx4 v[38:39], off
	v_lshl_add_u64 v[38:39], v[250:251], 0, s[70:71]
	s_mov_b32 m0, s83
	s_nop 0
	global_load_lds_dwordx4 v[38:39], off
	s_waitcnt vmcnt(8)
	s_waitcnt lgkmcnt(0)
	s_barrier
	s_setprio 1
	s_waitcnt lgkmcnt(0)
	v_mfma_f32_16x16x32_bf16 v[102:105], v[106:109], v[170:173], v[102:105]
	v_mfma_f32_16x16x32_bf16 v[30:33], v[114:117], v[170:173], v[30:33]
	v_mfma_f32_16x16x32_bf16 v[94:97], v[106:109], v[178:181], v[94:97]
	v_mfma_f32_16x16x32_bf16 v[22:25], v[114:117], v[178:181], v[22:25]
	v_mfma_f32_16x16x32_bf16 v[86:89], v[106:109], v[198:201], v[86:89]
	v_mfma_f32_16x16x32_bf16 v[14:17], v[114:117], v[198:201], v[14:17]
	v_mfma_f32_16x16x32_bf16 v[78:81], v[106:109], v[218:221], v[78:81]
	v_mfma_f32_16x16x32_bf16 v[6:9], v[114:117], v[218:221], v[6:9]
	v_mfma_f32_16x16x32_bf16 v[102:105], v[110:113], v[174:177], v[102:105]
	v_mfma_f32_16x16x32_bf16 v[30:33], v[118:121], v[174:177], v[30:33]
	v_mfma_f32_16x16x32_bf16 v[94:97], v[110:113], v[194:197], v[94:97]
	v_mfma_f32_16x16x32_bf16 v[22:25], v[118:121], v[194:197], v[22:25]
	v_mfma_f32_16x16x32_bf16 v[86:89], v[110:113], v[208:211], v[86:89]
	v_mfma_f32_16x16x32_bf16 v[14:17], v[118:121], v[208:211], v[14:17]
	v_mfma_f32_16x16x32_bf16 v[78:81], v[110:113], v[244:247], v[78:81]
	v_mfma_f32_16x16x32_bf16 v[6:9], v[118:121], v[244:247], v[6:9]
	s_setprio 0
	s_setprio 1
	v_mfma_f32_16x16x32_bf16 v[98:101], v[122:125], v[170:173], v[98:101]
	v_mfma_f32_16x16x32_bf16 v[26:29], v[130:133], v[170:173], v[26:29]
	v_mfma_f32_16x16x32_bf16 v[90:93], v[122:125], v[178:181], v[90:93]
	v_mfma_f32_16x16x32_bf16 v[18:21], v[130:133], v[178:181], v[18:21]
	v_mfma_f32_16x16x32_bf16 v[82:85], v[122:125], v[198:201], v[82:85]
	v_mfma_f32_16x16x32_bf16 v[10:13], v[130:133], v[198:201], v[10:13]
	v_mfma_f32_16x16x32_bf16 v[74:77], v[122:125], v[218:221], v[74:77]
	v_mfma_f32_16x16x32_bf16 v[2:5], v[130:133], v[218:221], v[2:5]
	v_mfma_f32_16x16x32_bf16 v[98:101], v[126:129], v[174:177], v[98:101]
	v_mfma_f32_16x16x32_bf16 v[26:29], v[134:137], v[174:177], v[26:29]
	v_mfma_f32_16x16x32_bf16 v[90:93], v[126:129], v[194:197], v[90:93]
	v_mfma_f32_16x16x32_bf16 v[18:21], v[134:137], v[194:197], v[18:21]
	v_mfma_f32_16x16x32_bf16 v[82:85], v[126:129], v[208:211], v[82:85]
	v_mfma_f32_16x16x32_bf16 v[10:13], v[134:137], v[208:211], v[10:13]
	v_mfma_f32_16x16x32_bf16 v[74:77], v[126:129], v[244:247], v[74:77]
	v_mfma_f32_16x16x32_bf16 v[2:5], v[134:137], v[244:247], v[2:5]
	s_setprio 0
	s_barrier
	s_add_i32 s17, s17, 2
	s_add_u32 s0, s0, 0x100
	s_addc_u32 s1, s1, 0
	s_add_u32 s15, s15, 0x100
	s_addc_u32 s16, s16, 0
	s_cmp_gt_u32 s17, 13
	s_cbranch_scc0 .LBB0_697
	v_readlane_b32 s0, v255, 13
	v_readlane_b32 s1, v255, 14
	s_and_b64 vcc, exec, s[0:1]
	s_cbranch_vccz .LBB0_702
	s_barrier
	s_cmpk_gt_i32 s18, 0x83
	s_mov_b64 s[0:1], -1
	s_cbranch_scc1 .LBB0_703
